# LN epilogues: row-statistics exchange buffer laid out slot-major so a wave's partial-sum stores/loads are contiguous 512 B
# speedup vs baseline: 1.0479x; 1.0248x over previous
.LBB0_94:
	s_mul_hi_u32 s23, s19, 0xaaaaaaab
	s_lshr_b32 s23, s23, 1
	s_mul_i32 s23, s23, 0x24000
	s_waitcnt lgkmcnt(0)
	v_mfma_f32_16x16x32_bf16 v[66:69], v[22:25], v[26:29], v[66:69]
	v_add_u32_e32 v222, s13, v113
	s_mul_hi_u32 s27, s14, 0xaaaaaaab
	s_lshr_b32 s27, s27, 1
	v_mfma_f32_16x16x32_bf16 v[62:65], v[18:21], v[26:29], v[62:65]
	s_mul_i32 s27, s27, 0x24000
	v_subrev_u32_e32 v182, s27, v126
	v_subrev_u32_e32 v191, s27, v127
	v_mfma_f32_16x16x32_bf16 v[58:61], v[10:13], v[26:29], v[58:61]
	v_subrev_u32_e32 v201, s27, v128
	v_mfma_f32_16x16x32_bf16 v[54:57], v[6:9], v[26:29], v[54:57]
	v_subrev_u32_e32 v26, s23, v125
	v_mfma_f32_16x16x32_bf16 v[50:53], v[22:25], v[14:17], v[50:53]
	v_mfma_f32_16x16x32_bf16 v[46:49], v[18:21], v[14:17], v[46:49]
	v_mfma_f32_16x16x32_bf16 v[42:45], v[10:13], v[14:17], v[42:45]
	v_mfma_f32_16x16x32_bf16 v[38:41], v[6:9], v[14:17], v[38:41]
	v_subrev_u32_e32 v14, s23, v129
	v_add_u32_e32 v16, v222, v26
	v_add_u32_e32 v14, v222, v14
	v_mfma_f32_16x16x32_bf16 v[34:37], v[22:25], v[30:33], v[34:37]
	v_subrev_u32_e32 v15, s27, v130
	v_mfma_f32_16x16x32_bf16 v[86:89], v[22:25], v[2:5], v[86:89]
	ds_read_b128 v[22:25], v16
	ds_read_b128 v[174:177], v16 offset:2048
	ds_read_b128 v[178:181], v16 offset:4096
	ds_read_b128 v[202:205], v16 offset:6144
	ds_read_b128 v[206:209], v14 offset:32768
	ds_read_b128 v[210:213], v14 offset:34816
	ds_read_b128 v[214:217], v14 offset:36864
	ds_read_b128 v[218:221], v14 offset:38912
	v_mfma_f32_16x16x32_bf16 v[74:77], v[18:21], v[30:33], v[74:77]
	v_mfma_f32_16x16x32_bf16 v[70:73], v[10:13], v[30:33], v[70:73]
	v_mfma_f32_16x16x32_bf16 v[78:81], v[6:9], v[30:33], v[78:81]
	v_mfma_f32_16x16x32_bf16 v[94:97], v[18:21], v[2:5], v[94:97]
	v_mfma_f32_16x16x32_bf16 v[90:93], v[10:13], v[2:5], v[90:93]
	v_mfma_f32_16x16x32_bf16 v[82:85], v[6:9], v[2:5], v[82:85]
	s_add_i32 s23, s6, 4
	s_mul_i32 s27, s23, 0xab
	s_bfe_u32 s27, s27, 0x70009
	s_mul_i32 s27, s27, 3
	s_sub_i32 s23, s23, s27
	s_and_b32 s23, s23, 0xff
	s_mul_i32 s23, s23, 0xc000
	s_waitcnt vmcnt(6)
	v_add_u32_e32 v2, v222, v15
	v_add_u32_e32 v6, v222, v201
	s_waitcnt lgkmcnt(0)
	v_mfma_f32_16x16x32_bf16 v[66:69], v[206:209], v[174:177], v[66:69]
	s_mov_b64 s[46:47], 0xbdd8180
	s_add_i32 s27, s23, s8
	s_waitcnt lgkmcnt(0)
	v_mfma_f32_16x16x32_bf16 v[62:65], v[210:213], v[174:177], v[62:65]
	s_barrier
	ds_read_b128 v[30:33], v2
	ds_read_b128 v[26:29], v2 offset:2048
	ds_read_b128 v[14:17], v2 offset:4096
	ds_read_b128 v[2:5], v2 offset:6144
	v_mfma_f32_16x16x32_bf16 v[58:61], v[214:217], v[174:177], v[58:61]
	v_add_u32_e32 v7, v222, v191
	s_mov_b32 m0, s27
	s_add_i32 s23, s23, s9
	v_mfma_f32_16x16x32_bf16 v[54:57], v[218:221], v[174:177], v[54:57]
	v_lshl_add_u64 v[174:175], v[108:109], 0, v[98:99]
	v_lshl_add_u64 v[176:177], v[174:175], 0, s[46:47]
	s_mov_b64 s[46:47], 0xbddc180
	v_mfma_f32_16x16x32_bf16 v[34:37], v[206:209], v[22:25], v[34:37]
	s_add_i32 s19, s19, 1
	v_mfma_f32_16x16x32_bf16 v[74:77], v[210:213], v[22:25], v[74:77]
	v_mfma_f32_16x16x32_bf16 v[70:73], v[214:217], v[22:25], v[70:73]
	v_mfma_f32_16x16x32_bf16 v[78:81], v[218:221], v[22:25], v[78:81]
	ds_read_b128 v[22:25], v6
	ds_read_b128 v[18:21], v7
	v_add_u32_e32 v6, v222, v182
	ds_read_b128 v[10:13], v6
	ds_read_b128 v[6:9], v6 offset:2048
	global_load_lds_dwordx4 v[176:177], off
	v_lshl_add_u64 v[176:177], v[174:175], 0, s[46:47]
	s_add_i32 m0, s27, 0x400
	s_mov_b64 s[46:47], 0xbde0180
	global_load_lds_dwordx4 v[176:177], off
	v_lshl_add_u64 v[176:177], v[174:175], 0, s[46:47]
	s_add_i32 m0, s27, 0x800
	s_mov_b64 s[46:47], 0xbde4180
	global_load_lds_dwordx4 v[176:177], off
	v_lshl_add_u64 v[174:175], v[174:175], 0, s[46:47]
	s_add_i32 m0, s27, 0xc00
	s_mov_b64 s[46:47], 0x1b00180
	global_load_lds_dwordx4 v[174:175], off
	v_lshl_add_u64 v[174:175], v[110:111], 0, v[98:99]
	v_lshl_add_u64 v[176:177], v[174:175], 0, s[46:47]
	s_add_i32 m0, s23, 0x8000
	s_mov_b64 s[46:47], 0x1b04180
	global_load_lds_dwordx4 v[176:177], off
	v_lshl_add_u64 v[174:175], v[174:175], 0, s[46:47]
	s_add_i32 m0, s23, 0x8400
	v_mfma_f32_16x16x32_bf16 v[50:53], v[206:209], v[178:181], v[50:53]
	global_load_lds_dwordx4 v[174:175], off
	v_mfma_f32_16x16x32_bf16 v[46:49], v[210:213], v[178:181], v[46:49]
	v_mfma_f32_16x16x32_bf16 v[42:45], v[214:217], v[178:181], v[42:45]
	v_mfma_f32_16x16x32_bf16 v[38:41], v[218:221], v[178:181], v[38:41]
	v_mfma_f32_16x16x32_bf16 v[86:89], v[206:209], v[202:205], v[86:89]
	v_mfma_f32_16x16x32_bf16 v[94:97], v[210:213], v[202:205], v[94:97]
	v_mfma_f32_16x16x32_bf16 v[90:93], v[214:217], v[202:205], v[90:93]
	v_mfma_f32_16x16x32_bf16 v[82:85], v[218:221], v[202:205], v[82:85]
	s_add_i32 s6, s6, 1
	s_add_i32 s13, s13, 0xc000
	s_add_i32 s14, s14, 1
	v_lshl_add_u64 v[108:109], v[108:109], 0, s[2:3]
	s_cmp_eq_u32 s13, 0x9c000
	v_lshl_add_u64 v[110:111], v[110:111], 0, s[2:3]
	s_cbranch_scc0 .LBB0_94
	s_waitcnt lgkmcnt(0)
	v_mfma_f32_16x16x32_bf16 v[34:37], v[22:25], v[30:33], v[34:37]
	v_mfma_f32_16x16x32_bf16 v[74:77], v[18:21], v[30:33], v[74:77]
	v_mfma_f32_16x16x32_bf16 v[70:73], v[10:13], v[30:33], v[70:73]
	v_mfma_f32_16x16x32_bf16 v[30:33], v[6:9], v[30:33], v[78:81]
	v_mfma_f32_16x16x32_bf16 v[66:69], v[22:25], v[26:29], v[66:69]
	v_mfma_f32_16x16x32_bf16 v[62:65], v[18:21], v[26:29], v[62:65]
	v_mfma_f32_16x16x32_bf16 v[58:61], v[10:13], v[26:29], v[58:61]
	v_mfma_f32_16x16x32_bf16 v[26:29], v[6:9], v[26:29], v[54:57]
	v_mfma_f32_16x16x32_bf16 v[50:53], v[22:25], v[14:17], v[50:53]
	v_mfma_f32_16x16x32_bf16 v[46:49], v[18:21], v[14:17], v[46:49]
	v_mfma_f32_16x16x32_bf16 v[42:45], v[10:13], v[14:17], v[42:45]
	v_mfma_f32_16x16x32_bf16 v[14:17], v[6:9], v[14:17], v[38:41]
	v_mfma_f32_16x16x32_bf16 v[22:25], v[22:25], v[2:5], v[86:89]
	s_nop 1
	ds_read_b128 v[38:41], v131
	ds_read_b128 v[54:57], v132 offset:2048
	ds_read_b128 v[78:81], v132 offset:4096
	ds_read_b128 v[86:89], v132 offset:6144
	v_mfma_f32_16x16x32_bf16 v[18:21], v[18:21], v[2:5], v[94:97]
	v_mfma_f32_16x16x32_bf16 v[10:13], v[10:13], v[2:5], v[90:93]
	s_nop 2
	ds_read_b128 v[90:93], v133 offset:32768
	ds_read_b128 v[94:97], v134 offset:34816
	ds_read_b128 v[108:111], v134 offset:36864
	ds_read_b128 v[174:177], v134 offset:38912
	v_mfma_f32_16x16x32_bf16 v[2:5], v[6:9], v[2:5], v[82:85]
	s_waitcnt lgkmcnt(0)
	v_mfma_f32_16x16x32_bf16 v[6:9], v[90:93], v[38:41], v[34:37]
	s_waitcnt vmcnt(6)
	s_waitcnt lgkmcnt(0)
	s_barrier
	v_mfma_f32_16x16x32_bf16 v[34:37], v[94:97], v[38:41], v[74:77]
	v_mfma_f32_16x16x32_bf16 v[70:73], v[108:111], v[38:41], v[70:73]
	v_mfma_f32_16x16x32_bf16 v[30:33], v[174:177], v[38:41], v[30:33]
	v_mfma_f32_16x16x32_bf16 v[38:41], v[90:93], v[54:57], v[66:69]
	v_mfma_f32_16x16x32_bf16 v[62:65], v[94:97], v[54:57], v[62:65]
	v_mfma_f32_16x16x32_bf16 v[58:61], v[108:111], v[54:57], v[58:61]
	v_mfma_f32_16x16x32_bf16 v[26:29], v[174:177], v[54:57], v[26:29]
	v_add_u32_e32 v54, v124, v115
	ds_read_b128 v[54:57], v54
	ds_read_b128 v[66:69], v135 offset:2048
	v_mfma_f32_16x16x32_bf16 v[50:53], v[90:93], v[78:81], v[50:53]
	v_mfma_f32_16x16x32_bf16 v[46:49], v[94:97], v[78:81], v[46:49]
	v_mfma_f32_16x16x32_bf16 v[42:45], v[108:111], v[78:81], v[42:45]
	v_mfma_f32_16x16x32_bf16 v[22:25], v[90:93], v[86:89], v[22:25]
	v_add_u32_e32 v90, 0x20800, v164
	v_mfma_f32_16x16x32_bf16 v[18:21], v[94:97], v[86:89], v[18:21]
	v_add_u32_e32 v94, 0x21000, v164
	v_mfma_f32_16x16x32_bf16 v[10:13], v[108:111], v[86:89], v[10:13]
	v_add_u32_e32 v108, 0x21800, v164
	v_mfma_f32_16x16x32_bf16 v[14:17], v[174:177], v[78:81], v[14:17]
	ds_read_b128 v[74:77], v135 offset:4096
	ds_read_b128 v[78:81], v135 offset:6144
	ds_read_b128 v[82:85], v163
	ds_read_b128 v[90:93], v90
	ds_read_b128 v[94:97], v94
	ds_read_b128 v[108:111], v108
	v_mfma_f32_16x16x32_bf16 v[2:5], v[174:177], v[86:89], v[2:5]
	s_waitcnt lgkmcnt(0)
	v_mfma_f32_16x16x32_bf16 v[6:9], v[82:85], v[54:57], v[6:9]
	v_mfma_f32_16x16x32_bf16 v[34:37], v[90:93], v[54:57], v[34:37]
	v_mfma_f32_16x16x32_bf16 v[70:73], v[94:97], v[54:57], v[70:73]
	v_mfma_f32_16x16x32_bf16 v[30:33], v[108:111], v[54:57], v[30:33]
	v_mfma_f32_16x16x32_bf16 v[54:57], v[90:93], v[66:69], v[62:65]
	s_nop 2
	v_add_u32_e32 v62, v124, v119
	v_mfma_f32_16x16x32_bf16 v[38:41], v[82:85], v[66:69], v[38:41]
	v_mfma_f32_16x16x32_bf16 v[58:61], v[94:97], v[66:69], v[58:61]
	v_mfma_f32_16x16x32_bf16 v[26:29], v[108:111], v[66:69], v[26:29]
	v_mfma_f32_16x16x32_bf16 v[50:53], v[82:85], v[74:77], v[50:53]
	v_mfma_f32_16x16x32_bf16 v[46:49], v[90:93], v[74:77], v[46:49]
	v_mfma_f32_16x16x32_bf16 v[42:45], v[94:97], v[74:77], v[42:45]
	v_mfma_f32_16x16x32_bf16 v[14:17], v[108:111], v[74:77], v[14:17]
	v_mfma_f32_16x16x32_bf16 v[22:25], v[82:85], v[78:81], v[22:25]
	ds_read_b128 v[62:65], v62
	ds_read_b128 v[66:69], v165
	ds_read_b128 v[74:77], v166
	ds_read_b128 v[82:85], v167
	v_mfma_f32_16x16x32_bf16 v[18:21], v[90:93], v[78:81], v[18:21]
	v_mfma_f32_16x16x32_bf16 v[10:13], v[94:97], v[78:81], v[10:13]
	ds_read_b128 v[86:89], v168
	ds_read_b128 v[90:93], v169
	ds_read_b128 v[94:97], v170
	ds_read_b128 v[174:177], v171
	v_mfma_f32_16x16x32_bf16 v[2:5], v[108:111], v[78:81], v[2:5]
	s_waitcnt vmcnt(0)
	s_waitcnt lgkmcnt(0)
	v_mfma_f32_16x16x32_bf16 v[6:9], v[86:89], v[62:65], v[6:9]
	s_waitcnt lgkmcnt(0)
	s_barrier
	v_mfma_f32_16x16x32_bf16 v[34:37], v[90:93], v[62:65], v[34:37]
	v_mfma_f32_16x16x32_bf16 v[70:73], v[94:97], v[62:65], v[70:73]
	v_mfma_f32_16x16x32_bf16 v[30:33], v[174:177], v[62:65], v[30:33]
	v_mfma_f32_16x16x32_bf16 v[38:41], v[86:89], v[66:69], v[38:41]
	v_mfma_f32_16x16x32_bf16 v[54:57], v[90:93], v[66:69], v[54:57]
	v_mfma_f32_16x16x32_bf16 v[58:61], v[94:97], v[66:69], v[58:61]
	v_mfma_f32_16x16x32_bf16 v[26:29], v[174:177], v[66:69], v[26:29]
	v_mfma_f32_16x16x32_bf16 v[50:53], v[86:89], v[74:77], v[50:53]
	v_mfma_f32_16x16x32_bf16 v[46:49], v[90:93], v[74:77], v[46:49]
	v_mfma_f32_16x16x32_bf16 v[42:45], v[94:97], v[74:77], v[42:45]
	v_mfma_f32_16x16x32_bf16 v[14:17], v[174:177], v[74:77], v[14:17]
	ds_read_b128 v[62:65], v164 offset:38912
	ds_read_b128 v[66:69], v164 offset:36864
	ds_read_b128 v[74:77], v164 offset:34816
	ds_read_b128 v[78:81], v161 offset:32768
	v_mfma_f32_16x16x32_bf16 v[22:25], v[86:89], v[82:85], v[22:25]
	v_mfma_f32_16x16x32_bf16 v[18:21], v[90:93], v[82:85], v[18:21]
	v_mfma_f32_16x16x32_bf16 v[10:13], v[94:97], v[82:85], v[10:13]
	ds_read_b128 v[86:89], v173 offset:6144
	ds_read_b128 v[90:93], v173 offset:4096
	ds_read_b128 v[94:97], v173 offset:2048
	ds_read_b128 v[108:111], v172
	v_mfma_f32_16x16x32_bf16 v[2:5], v[174:177], v[82:85], v[2:5]
	s_waitcnt lgkmcnt(0)
	v_mfma_f32_16x16x32_bf16 v[38:41], v[78:81], v[94:97], v[38:41]
	v_add_u32_e32 v82, v114, v119
	v_add_u32_e32 v172, v118, v119
	v_mfma_f32_16x16x32_bf16 v[54:57], v[74:77], v[94:97], v[54:57]
	v_mfma_f32_16x16x32_bf16 v[58:61], v[66:69], v[94:97], v[58:61]
	v_mfma_f32_16x16x32_bf16 v[26:29], v[62:65], v[94:97], v[26:29]
	v_add_u32_e32 v94, v117, v119
	v_mfma_f32_16x16x32_bf16 v[50:53], v[78:81], v[90:93], v[50:53]
	v_mfma_f32_16x16x32_bf16 v[46:49], v[74:77], v[90:93], v[46:49]
	v_mfma_f32_16x16x32_bf16 v[42:45], v[66:69], v[90:93], v[42:45]
	v_mfma_f32_16x16x32_bf16 v[14:17], v[62:65], v[90:93], v[14:17]
	v_add_u32_e32 v90, v116, v119
	v_mfma_f32_16x16x32_bf16 v[6:9], v[78:81], v[108:111], v[6:9]
	v_mfma_f32_16x16x32_bf16 v[34:37], v[74:77], v[108:111], v[34:37]
	v_mfma_f32_16x16x32_bf16 v[70:73], v[66:69], v[108:111], v[70:73]
	v_mfma_f32_16x16x32_bf16 v[30:33], v[62:65], v[108:111], v[30:33]
	v_mfma_f32_16x16x32_bf16 v[78:81], v[78:81], v[86:89], v[22:25]
	s_nop 2
	ds_read_b128 v[22:25], v82
	ds_read_b128 v[82:85], v90 offset:2048
	v_mfma_f32_16x16x32_bf16 v[74:77], v[74:77], v[86:89], v[18:21]
	s_nop 2
	ds_read_b128 v[18:21], v90 offset:4096
	ds_read_b128 v[90:93], v90 offset:6144
	v_mfma_f32_16x16x32_bf16 v[66:69], v[66:69], v[86:89], v[10:13]
	s_nop 2
	ds_read_b128 v[10:13], v94 offset:32768
	ds_read_b128 v[94:97], v172 offset:34816
	ds_read_b128 v[108:111], v172 offset:36864
	ds_read_b128 v[172:175], v172 offset:38912
	v_mfma_f32_16x16x32_bf16 v[2:5], v[62:65], v[86:89], v[2:5]
	s_waitcnt vmcnt(0)
	s_waitcnt lgkmcnt(0)
	v_mfma_f32_16x16x32_bf16 v[2:5], v[172:175], v[90:93], v[2:5]
	s_waitcnt lgkmcnt(0)
	s_barrier
	v_mfma_f32_16x16x32_bf16 v[62:65], v[10:13], v[22:25], v[6:9]
	v_mfma_f32_16x16x32_bf16 v[86:89], v[94:97], v[22:25], v[34:37]
	v_mfma_f32_16x16x32_bf16 v[70:73], v[108:111], v[22:25], v[70:73]
	v_mfma_f32_16x16x32_bf16 v[176:179], v[172:175], v[22:25], v[30:33]
	v_mfma_f32_16x16x32_bf16 v[202:205], v[10:13], v[82:85], v[38:41]
	v_mfma_f32_16x16x32_bf16 v[54:57], v[94:97], v[82:85], v[54:57]
	v_mfma_f32_16x16x32_bf16 v[58:61], v[108:111], v[82:85], v[58:61]
	v_mfma_f32_16x16x32_bf16 v[34:37], v[172:175], v[82:85], v[26:29]
	v_mfma_f32_16x16x32_bf16 v[30:33], v[10:13], v[18:21], v[50:53]
	v_mfma_f32_16x16x32_bf16 v[26:29], v[94:97], v[18:21], v[46:49]
	v_mfma_f32_16x16x32_bf16 v[22:25], v[108:111], v[18:21], v[42:45]
	v_mfma_f32_16x16x32_bf16 v[18:21], v[172:175], v[18:21], v[14:17]
	v_mfma_f32_16x16x32_bf16 v[14:17], v[10:13], v[90:93], v[78:81]
	v_mfma_f32_16x16x32_bf16 v[10:13], v[94:97], v[90:93], v[74:77]
	v_mfma_f32_16x16x32_bf16 v[6:9], v[108:111], v[90:93], v[66:69]
	s_mul_hi_i32 s64, s60, 0x2aaaaaab
	s_lshr_b32 s65, s64, 31
	s_ashr_i32 s64, s64, 2
	s_add_i32 s6, s64, s65
	s_mul_i32 s64, s6, 24
	s_sub_i32 s13, s60, s64
	v_readfirstlane_b32 s64, v137
	s_lshr_b32 s64, s64, 6
	s_and_b32 s14, s64, 1
	s_lshr_b32 s64, s64, 1
	s_lshl_b32 s64, s64, 6
	s_lshl_b32 s36, s13, 8
	s_add_i32 s36, s36, s64
	s_lshl_b32 s37, s6, 7
	s_lshl_b32 s64, s14, 6
	s_add_i32 s37, s37, s64
	s_add_i32 s64, s36, 0xfffff000
	s_ashr_i32 s64, s64, 10
	s_add_i32 s64, s64, 1
	s_cmpk_lt_i32 s36, 0x1000
	s_cselect_b32 s52, 0, s64
	v_readlane_b32 s53, v255, 40
	v_and_b32_e32 v250, 63, v137
	v_and_b32_e32 v251, 15, v250
	v_lshrrev_b32_e32 v252, 4, v250
	s_mul_i32 s64, s53, 3
	s_add_i32 s64, s64, s52
	s_mul_i32 s64, s64, 0x6000
	s_add_u32 s22, s94, 0x6300000
	s_addc_u32 s23, s95, 0
	s_add_u32 s22, s22, s64
	s_addc_u32 s23, s23, 0
	s_add_u32 s26, s94, 0x6348000
	s_addc_u32 s27, s95, 0
	v_add_u32_e32 v242, s36, v251
	v_lshlrev_b32_e32 v242, 12, v242
	s_lshl_b32 s64, s37, 2
	v_lshl_add_u32 v242, v252, 4, v242
	v_add_u32_e32 v242, s64, v242
	s_add_i32 s65, s37, 2048
	s_lshl_b32 s65, s65, 2
	v_lshl_add_u32 v246, v252, 4, s65
	v_add_u32_e32 v243, 0x10000, v242
	v_add_u32_e32 v244, 0x20000, v242
	v_add_u32_e32 v245, 0x30000, v242
	global_load_dwordx4 v[226:229], v246, s[22:23]
	global_load_dwordx4 v[230:233], v246, s[22:23] offset:64
	global_load_dwordx4 v[234:237], v246, s[22:23] offset:128
	global_load_dwordx4 v[238:241], v246, s[22:23] offset:192
	global_load_dwordx4 v[38:41], v242, s[26:27]
	global_load_dwordx4 v[42:45], v242, s[26:27] offset:64
	global_load_dwordx4 v[46:49], v242, s[26:27] offset:128
	global_load_dwordx4 v[50:53], v242, s[26:27] offset:192
	global_load_dwordx4 v[66:69], v243, s[26:27]
	global_load_dwordx4 v[74:77], v243, s[26:27] offset:64
	global_load_dwordx4 v[78:81], v243, s[26:27] offset:128
	global_load_dwordx4 v[82:85], v243, s[26:27] offset:192
	global_load_dwordx4 v[90:93], v244, s[26:27]
	global_load_dwordx4 v[94:97], v244, s[26:27] offset:64
	global_load_dwordx4 v[108:111], v244, s[26:27] offset:128
	global_load_dwordx4 v[172:175], v244, s[26:27] offset:192
	global_load_dwordx4 v[206:209], v245, s[26:27]
	global_load_dwordx4 v[210:213], v245, s[26:27] offset:64
	global_load_dwordx4 v[214:217], v245, s[26:27] offset:128
	global_load_dwordx4 v[218:221], v245, s[26:27] offset:192
	v_mov_b32_e32 v248, 0x3fd744fd
	v_mov_b32_e32 v249, 0x3fd744fd
	s_waitcnt vmcnt(12)
	v_pk_mul_f32 v[38:39], v[38:39], v[248:249]
	v_pk_mul_f32 v[40:41], v[40:41], v[248:249]
	v_pk_fma_f32 v[62:63], v[62:63], v[226:227], v[38:39]
	v_pk_fma_f32 v[64:65], v[64:65], v[228:229], v[40:41]
	v_pk_mul_f32 v[42:43], v[42:43], v[248:249]
	v_pk_mul_f32 v[44:45], v[44:45], v[248:249]
	v_pk_fma_f32 v[86:87], v[86:87], v[230:231], v[42:43]
	v_pk_fma_f32 v[88:89], v[88:89], v[232:233], v[44:45]
	v_pk_mul_f32 v[46:47], v[46:47], v[248:249]
	v_pk_mul_f32 v[48:49], v[48:49], v[248:249]
	v_pk_fma_f32 v[70:71], v[70:71], v[234:235], v[46:47]
	v_pk_fma_f32 v[72:73], v[72:73], v[236:237], v[48:49]
	v_pk_mul_f32 v[50:51], v[50:51], v[248:249]
	v_pk_mul_f32 v[52:53], v[52:53], v[248:249]
	v_pk_fma_f32 v[176:177], v[176:177], v[238:239], v[50:51]
	v_pk_fma_f32 v[178:179], v[178:179], v[240:241], v[52:53]
	s_waitcnt vmcnt(8)
	v_pk_mul_f32 v[66:67], v[66:67], v[248:249]
	v_pk_mul_f32 v[68:69], v[68:69], v[248:249]
	v_pk_fma_f32 v[202:203], v[202:203], v[226:227], v[66:67]
	v_pk_fma_f32 v[204:205], v[204:205], v[228:229], v[68:69]
	v_pk_mul_f32 v[74:75], v[74:75], v[248:249]
	v_pk_mul_f32 v[76:77], v[76:77], v[248:249]
	v_pk_fma_f32 v[54:55], v[54:55], v[230:231], v[74:75]
	v_pk_fma_f32 v[56:57], v[56:57], v[232:233], v[76:77]
	v_pk_mul_f32 v[78:79], v[78:79], v[248:249]
	v_pk_mul_f32 v[80:81], v[80:81], v[248:249]
	v_pk_fma_f32 v[58:59], v[58:59], v[234:235], v[78:79]
	v_pk_fma_f32 v[60:61], v[60:61], v[236:237], v[80:81]
	v_pk_mul_f32 v[82:83], v[82:83], v[248:249]
	v_pk_mul_f32 v[84:85], v[84:85], v[248:249]
	v_pk_fma_f32 v[34:35], v[34:35], v[238:239], v[82:83]
	v_pk_fma_f32 v[36:37], v[36:37], v[240:241], v[84:85]
	s_waitcnt vmcnt(4)
	v_pk_mul_f32 v[90:91], v[90:91], v[248:249]
	v_pk_mul_f32 v[92:93], v[92:93], v[248:249]
	v_pk_fma_f32 v[30:31], v[30:31], v[226:227], v[90:91]
	v_pk_fma_f32 v[32:33], v[32:33], v[228:229], v[92:93]
	v_pk_mul_f32 v[94:95], v[94:95], v[248:249]
	v_pk_mul_f32 v[96:97], v[96:97], v[248:249]
	v_pk_fma_f32 v[26:27], v[26:27], v[230:231], v[94:95]
	v_pk_fma_f32 v[28:29], v[28:29], v[232:233], v[96:97]
	v_pk_mul_f32 v[108:109], v[108:109], v[248:249]
	v_pk_mul_f32 v[110:111], v[110:111], v[248:249]
	v_pk_fma_f32 v[22:23], v[22:23], v[234:235], v[108:109]
	v_pk_fma_f32 v[24:25], v[24:25], v[236:237], v[110:111]
	v_pk_mul_f32 v[172:173], v[172:173], v[248:249]
	v_pk_mul_f32 v[174:175], v[174:175], v[248:249]
	v_pk_fma_f32 v[18:19], v[18:19], v[238:239], v[172:173]
	v_pk_fma_f32 v[20:21], v[20:21], v[240:241], v[174:175]
	s_waitcnt vmcnt(0)
	v_pk_mul_f32 v[206:207], v[206:207], v[248:249]
	v_pk_mul_f32 v[208:209], v[208:209], v[248:249]
	v_pk_fma_f32 v[14:15], v[14:15], v[226:227], v[206:207]
	v_pk_fma_f32 v[16:17], v[16:17], v[228:229], v[208:209]
	v_pk_mul_f32 v[210:211], v[210:211], v[248:249]
	v_pk_mul_f32 v[212:213], v[212:213], v[248:249]
	v_pk_fma_f32 v[10:11], v[10:11], v[230:231], v[210:211]
	v_pk_fma_f32 v[12:13], v[12:13], v[232:233], v[212:213]
	v_pk_mul_f32 v[214:215], v[214:215], v[248:249]
	v_pk_mul_f32 v[216:217], v[216:217], v[248:249]
	v_pk_fma_f32 v[6:7], v[6:7], v[234:235], v[214:215]
	v_pk_fma_f32 v[8:9], v[8:9], v[236:237], v[216:217]
	v_pk_mul_f32 v[218:219], v[218:219], v[248:249]
	v_pk_mul_f32 v[220:221], v[220:221], v[248:249]
	v_pk_fma_f32 v[2:3], v[2:3], v[238:239], v[218:219]
	v_pk_fma_f32 v[4:5], v[4:5], v[240:241], v[220:221]
	v_pk_mul_f32 v[208:209], v[62:63], v[62:63]
	v_pk_add_f32 v[206:207], v[62:63], v[64:65]
	v_pk_fma_f32 v[208:209], v[64:65], v[64:65], v[208:209]
	v_pk_add_f32 v[206:207], v[206:207], v[86:87]
	v_pk_fma_f32 v[208:209], v[86:87], v[86:87], v[208:209]
	v_pk_add_f32 v[206:207], v[206:207], v[88:89]
	v_pk_fma_f32 v[208:209], v[88:89], v[88:89], v[208:209]
	v_pk_add_f32 v[206:207], v[206:207], v[70:71]
	v_pk_fma_f32 v[208:209], v[70:71], v[70:71], v[208:209]
	v_pk_add_f32 v[206:207], v[206:207], v[72:73]
	v_pk_fma_f32 v[208:209], v[72:73], v[72:73], v[208:209]
	v_pk_add_f32 v[206:207], v[206:207], v[176:177]
	v_pk_fma_f32 v[208:209], v[176:177], v[176:177], v[208:209]
	v_pk_add_f32 v[206:207], v[206:207], v[178:179]
	v_pk_fma_f32 v[208:209], v[178:179], v[178:179], v[208:209]
	v_add_f32_e32 v206, v206, v207
	v_add_f32_e32 v208, v208, v209
	v_pk_mul_f32 v[212:213], v[202:203], v[202:203]
	v_pk_add_f32 v[210:211], v[202:203], v[204:205]
	v_pk_fma_f32 v[212:213], v[204:205], v[204:205], v[212:213]
	v_pk_add_f32 v[210:211], v[210:211], v[54:55]
	v_pk_fma_f32 v[212:213], v[54:55], v[54:55], v[212:213]
	v_pk_add_f32 v[210:211], v[210:211], v[56:57]
	v_pk_fma_f32 v[212:213], v[56:57], v[56:57], v[212:213]
	v_pk_add_f32 v[210:211], v[210:211], v[58:59]
	v_pk_fma_f32 v[212:213], v[58:59], v[58:59], v[212:213]
	v_pk_add_f32 v[210:211], v[210:211], v[60:61]
	v_pk_fma_f32 v[212:213], v[60:61], v[60:61], v[212:213]
	v_pk_add_f32 v[210:211], v[210:211], v[34:35]
	v_pk_fma_f32 v[212:213], v[34:35], v[34:35], v[212:213]
	v_pk_add_f32 v[210:211], v[210:211], v[36:37]
	v_pk_fma_f32 v[212:213], v[36:37], v[36:37], v[212:213]
	v_add_f32_e32 v210, v210, v211
	v_add_f32_e32 v212, v212, v213
	v_pk_mul_f32 v[216:217], v[30:31], v[30:31]
	v_pk_add_f32 v[214:215], v[30:31], v[32:33]
	v_pk_fma_f32 v[216:217], v[32:33], v[32:33], v[216:217]
	v_pk_add_f32 v[214:215], v[214:215], v[26:27]
	v_pk_fma_f32 v[216:217], v[26:27], v[26:27], v[216:217]
	v_pk_add_f32 v[214:215], v[214:215], v[28:29]
	v_pk_fma_f32 v[216:217], v[28:29], v[28:29], v[216:217]
	v_pk_add_f32 v[214:215], v[214:215], v[22:23]
	v_pk_fma_f32 v[216:217], v[22:23], v[22:23], v[216:217]
	v_pk_add_f32 v[214:215], v[214:215], v[24:25]
	v_pk_fma_f32 v[216:217], v[24:25], v[24:25], v[216:217]
	v_pk_add_f32 v[214:215], v[214:215], v[18:19]
	v_pk_fma_f32 v[216:217], v[18:19], v[18:19], v[216:217]
	v_pk_add_f32 v[214:215], v[214:215], v[20:21]
	v_pk_fma_f32 v[216:217], v[20:21], v[20:21], v[216:217]
	v_add_f32_e32 v214, v214, v215
	v_add_f32_e32 v216, v216, v217
	v_pk_mul_f32 v[220:221], v[14:15], v[14:15]
	v_pk_add_f32 v[218:219], v[14:15], v[16:17]
	v_pk_fma_f32 v[220:221], v[16:17], v[16:17], v[220:221]
	v_pk_add_f32 v[218:219], v[218:219], v[10:11]
	v_pk_fma_f32 v[220:221], v[10:11], v[10:11], v[220:221]
	v_pk_add_f32 v[218:219], v[218:219], v[12:13]
	v_pk_fma_f32 v[220:221], v[12:13], v[12:13], v[220:221]
	v_pk_add_f32 v[218:219], v[218:219], v[6:7]
	v_pk_fma_f32 v[220:221], v[6:7], v[6:7], v[220:221]
	v_pk_add_f32 v[218:219], v[218:219], v[8:9]
	v_pk_fma_f32 v[220:221], v[8:9], v[8:9], v[220:221]
	v_pk_add_f32 v[218:219], v[218:219], v[2:3]
	v_pk_fma_f32 v[220:221], v[2:3], v[2:3], v[220:221]
	v_pk_add_f32 v[218:219], v[218:219], v[4:5]
	v_pk_fma_f32 v[220:221], v[4:5], v[4:5], v[220:221]
	v_add_f32_e32 v218, v218, v219
	v_add_f32_e32 v220, v220, v221
	s_nop 1
	v_permlane16_swap_b32_e32 v206, v210
	v_permlane16_swap_b32_e32 v214, v218
	v_permlane16_swap_b32_e32 v208, v212
	v_permlane16_swap_b32_e32 v216, v220
	v_add_f32_e32 v206, v206, v210
	v_add_f32_e32 v214, v214, v218
	v_add_f32_e32 v208, v208, v212
	v_add_f32_e32 v216, v216, v220
	s_nop 1
	v_permlane32_swap_b32_e32 v206, v214
	v_permlane32_swap_b32_e32 v208, v216
	v_add_f32_e32 v248, v206, v214
	v_add_f32_e32 v249, v208, v216
	s_add_u32 s44, s94, 0x11e5e100
	s_addc_u32 s45, s95, 0
	v_add_u32_e32 v247, s36, v250
	v_lshlrev_b32_e32 v247, 3, v247
	s_lshl_b32 s64, s6, 1
	s_add_i32 s64, s64, s14
	s_mul_i32 s64, s64, 0xc000
	v_add_u32_e32 v246, s64, v247
	global_store_dwordx2 v246, v[248:249], s[44:45] sc1
	v_readlane_b32 s46, v253, 11
	v_readlane_b32 s47, v253, 12
	v_readlane_b32 s48, v253, 13
	v_readlane_b32 s49, v253, 14
	s_lshl_b32 s64, s53, 10
	s_add_i32 s64, s64, s37
	s_lshl_b32 s64, s64, 2
	v_lshl_add_u32 v222, v252, 4, s64
	s_nop 3
	global_load_dwordx4 v[66:69], v222, s[46:47]
	global_load_dwordx4 v[74:77], v222, s[46:47] offset:64
	global_load_dwordx4 v[78:81], v222, s[46:47] offset:128
	global_load_dwordx4 v[82:85], v222, s[46:47] offset:192
	global_load_dwordx4 v[90:93], v222, s[48:49]
	global_load_dwordx4 v[94:97], v222, s[48:49] offset:64
	global_load_dwordx4 v[108:111], v222, s[48:49] offset:128
	global_load_dwordx4 v[172:175], v222, s[48:49] offset:192
	s_waitcnt vmcnt(8)
	s_barrier
	v_cmp_eq_u32_e64 s[46:47], 0, v137
	s_nop 3
	s_and_saveexec_b64 s[48:49], s[46:47]
	s_cbranch_execz .Lln1_xdone
	s_mul_i32 s64, s53, 384
	s_lshl_b32 s65, s13, 2
	s_add_i32 s64, s64, s65
	s_add_u32 s46, s94, 0x11e5d700
	s_addc_u32 s47, s95, 0
	s_add_u32 s46, s46, s64
	s_addc_u32 s47, s47, 0
	v_mov_b32_e32 v248, 1
	s_mov_b32 s65, 0x100000
	global_atomic_add v1, v248, s[46:47]

.Lln1_xdone:
	s_or_b64 exec, exec, s[48:49]
	s_barrier
	global_load_dwordx2 v[226:227], v247, s[44:45] sc1
	s_add_u32 s44, s44, 0xc000
	s_addc_u32 s45, s45, 0
	global_load_dwordx2 v[228:229], v247, s[44:45] sc1
	s_add_u32 s44, s44, 0xc000
	s_addc_u32 s45, s45, 0
	global_load_dwordx2 v[230:231], v247, s[44:45] sc1
	s_add_u32 s44, s44, 0xc000
	s_addc_u32 s45, s45, 0
	global_load_dwordx2 v[232:233], v247, s[44:45] sc1
	s_add_u32 s44, s44, 0xc000
	s_addc_u32 s45, s45, 0
	global_load_dwordx2 v[234:235], v247, s[44:45] sc1
	s_add_u32 s44, s44, 0xc000
	s_addc_u32 s45, s45, 0
	global_load_dwordx2 v[236:237], v247, s[44:45] sc1
	s_add_u32 s44, s44, 0xc000
	s_addc_u32 s45, s45, 0
	global_load_dwordx2 v[238:239], v247, s[44:45] sc1
	s_add_u32 s44, s44, 0xc000
	s_addc_u32 s45, s45, 0
	global_load_dwordx2 v[240:241], v247, s[44:45] sc1
	s_add_u32 s44, s44, 0xc000
	s_addc_u32 s45, s45, 0
	global_load_dwordx2 v[38:39], v247, s[44:45] sc1
	s_add_u32 s44, s44, 0xc000
	s_addc_u32 s45, s45, 0
	global_load_dwordx2 v[40:41], v247, s[44:45] sc1
	s_add_u32 s44, s44, 0xc000
	s_addc_u32 s45, s45, 0
	global_load_dwordx2 v[42:43], v247, s[44:45] sc1
	s_add_u32 s44, s44, 0xc000
	s_addc_u32 s45, s45, 0
	global_load_dwordx2 v[44:45], v247, s[44:45] sc1
	s_add_u32 s44, s44, 0xc000
	s_addc_u32 s45, s45, 0
	global_load_dwordx2 v[46:47], v247, s[44:45] sc1
	s_add_u32 s44, s44, 0xc000
	s_addc_u32 s45, s45, 0
	global_load_dwordx2 v[48:49], v247, s[44:45] sc1
	s_add_u32 s44, s44, 0xc000
	s_addc_u32 s45, s45, 0
	global_load_dwordx2 v[50:51], v247, s[44:45] sc1
	s_add_u32 s44, s44, 0xc000
	s_addc_u32 s45, s45, 0
	global_load_dwordx2 v[52:53], v247, s[44:45] sc1
	s_waitcnt vmcnt(0)
	v_add_f32_e32 v206, 0, v226
	v_add_f32_e32 v207, 0, v227
	v_add_f32_e32 v206, v206, v228
	v_add_f32_e32 v207, v207, v229
	v_add_f32_e32 v206, v206, v230
	v_add_f32_e32 v207, v207, v231
	v_add_f32_e32 v206, v206, v232
	v_add_f32_e32 v207, v207, v233
	v_add_f32_e32 v206, v206, v234
	v_add_f32_e32 v207, v207, v235
	v_add_f32_e32 v206, v206, v236
	v_add_f32_e32 v207, v207, v237
	v_add_f32_e32 v206, v206, v238
	v_add_f32_e32 v207, v207, v239
	v_add_f32_e32 v206, v206, v240
	v_add_f32_e32 v207, v207, v241
	v_add_f32_e32 v206, v206, v38
	v_add_f32_e32 v207, v207, v39
	v_add_f32_e32 v206, v206, v40
	v_add_f32_e32 v207, v207, v41
	v_add_f32_e32 v206, v206, v42
	v_add_f32_e32 v207, v207, v43
	v_add_f32_e32 v206, v206, v44
	v_add_f32_e32 v207, v207, v45
	v_add_f32_e32 v206, v206, v46
	v_add_f32_e32 v207, v207, v47
	v_add_f32_e32 v206, v206, v48
	v_add_f32_e32 v207, v207, v49
	v_add_f32_e32 v206, v206, v50
	v_add_f32_e32 v207, v207, v51
	v_add_f32_e32 v206, v206, v52
	v_add_f32_e32 v207, v207, v53
	s_add_i32 s64, s37, 3072
	s_lshl_b32 s64, s64, 2
	v_lshl_add_u32 v222, v252, 4, s64
	v_add_u32_e32 v246, 0x1000, v222
	global_load_dwordx4 v[226:229], v222, s[22:23]
	global_load_dwordx4 v[230:233], v222, s[22:23] offset:64
	global_load_dwordx4 v[234:237], v222, s[22:23] offset:128
	global_load_dwordx4 v[238:241], v222, s[22:23] offset:192
	global_load_dwordx4 v[38:41], v246, s[22:23]
	global_load_dwordx4 v[42:45], v246, s[22:23] offset:64
	global_load_dwordx4 v[46:49], v246, s[22:23] offset:128
	global_load_dwordx4 v[50:53], v246, s[22:23] offset:192
	v_mul_f32_e32 v208, 0x3a800000, v206
	v_mul_f32_e32 v209, v208, v208
	v_mov_b32_e32 v216, 0x3a800000
	v_fma_f32 v209, v207, v216, -v209
	v_max_f32_e32 v209, 0, v209
	v_add_f32_e32 v209, 0x3727c5ac, v209
	v_rsq_f32_e32 v209, v209
	v_mov_b32_e32 v210, v208
	v_mov_b32_e32 v211, v208
	v_mov_b32_e32 v214, v209
	v_mov_b32_e32 v215, v209
	s_nop 1
	v_permlane16_swap_b32_e32 v210, v211
	v_permlane16_swap_b32_e32 v214, v215
	v_mov_b32_e32 v212, v210
	v_mov_b32_e32 v213, v211
	v_mov_b32_e32 v216, v214
	v_mov_b32_e32 v217, v215
	s_nop 1
	v_permlane32_swap_b32_e32 v210, v212
	v_permlane32_swap_b32_e32 v211, v213
	v_permlane32_swap_b32_e32 v214, v216
	v_permlane32_swap_b32_e32 v215, v217
	v_sub_f32_e32 v62, v62, v210
	v_sub_f32_e32 v63, v63, v210
	v_sub_f32_e32 v64, v64, v210
	v_sub_f32_e32 v65, v65, v210
	v_mul_f32_e32 v62, v214, v62
	v_mul_f32_e32 v63, v214, v63
	v_mul_f32_e32 v64, v214, v64
	v_mul_f32_e32 v65, v214, v65
	v_fma_f32 v62, v66, v62, v90
	v_fma_f32 v63, v67, v63, v91
	v_fma_f32 v64, v68, v64, v92
	v_fma_f32 v65, v69, v65, v93
	global_store_dwordx4 v242, v[62:65], s[26:27]
	v_sub_f32_e32 v86, v86, v210
	v_sub_f32_e32 v87, v87, v210
	v_sub_f32_e32 v88, v88, v210
	v_sub_f32_e32 v89, v89, v210
	v_mul_f32_e32 v86, v214, v86
	v_mul_f32_e32 v87, v214, v87
	v_mul_f32_e32 v88, v214, v88
	v_mul_f32_e32 v89, v214, v89
	v_fma_f32 v86, v74, v86, v94
	v_fma_f32 v87, v75, v87, v95
	v_fma_f32 v88, v76, v88, v96
	v_fma_f32 v89, v77, v89, v97
	global_store_dwordx4 v242, v[86:89], s[26:27] offset:64
	v_sub_f32_e32 v70, v70, v210
	v_sub_f32_e32 v71, v71, v210
	v_sub_f32_e32 v72, v72, v210
	v_sub_f32_e32 v73, v73, v210
	v_mul_f32_e32 v70, v214, v70
	v_mul_f32_e32 v71, v214, v71
	v_mul_f32_e32 v72, v214, v72
	v_mul_f32_e32 v73, v214, v73
	v_fma_f32 v70, v78, v70, v108
	v_fma_f32 v71, v79, v71, v109
	v_fma_f32 v72, v80, v72, v110
	v_fma_f32 v73, v81, v73, v111
	global_store_dwordx4 v242, v[70:73], s[26:27] offset:128
	v_sub_f32_e32 v176, v176, v210
	v_sub_f32_e32 v177, v177, v210
	v_sub_f32_e32 v178, v178, v210
	v_sub_f32_e32 v179, v179, v210
	v_mul_f32_e32 v176, v214, v176
	v_mul_f32_e32 v177, v214, v177
	v_mul_f32_e32 v178, v214, v178
	v_mul_f32_e32 v179, v214, v179
	v_fma_f32 v176, v82, v176, v172
	v_fma_f32 v177, v83, v177, v173
	v_fma_f32 v178, v84, v178, v174
	v_fma_f32 v179, v85, v179, v175
	global_store_dwordx4 v242, v[176:179], s[26:27] offset:192
	v_sub_f32_e32 v202, v202, v211
	v_sub_f32_e32 v203, v203, v211
	v_sub_f32_e32 v204, v204, v211
	v_sub_f32_e32 v205, v205, v211
	v_mul_f32_e32 v202, v215, v202
	v_mul_f32_e32 v203, v215, v203
	v_mul_f32_e32 v204, v215, v204
	v_mul_f32_e32 v205, v215, v205
	v_fma_f32 v202, v66, v202, v90
	v_fma_f32 v203, v67, v203, v91
	v_fma_f32 v204, v68, v204, v92
	v_fma_f32 v205, v69, v205, v93
	global_store_dwordx4 v243, v[202:205], s[26:27]
	v_sub_f32_e32 v54, v54, v211
	v_sub_f32_e32 v55, v55, v211
	v_sub_f32_e32 v56, v56, v211
	v_sub_f32_e32 v57, v57, v211
	v_mul_f32_e32 v54, v215, v54
	v_mul_f32_e32 v55, v215, v55
	v_mul_f32_e32 v56, v215, v56
	v_mul_f32_e32 v57, v215, v57
	v_fma_f32 v54, v74, v54, v94
	v_fma_f32 v55, v75, v55, v95
	v_fma_f32 v56, v76, v56, v96
	v_fma_f32 v57, v77, v57, v97
	global_store_dwordx4 v243, v[54:57], s[26:27] offset:64
	v_sub_f32_e32 v58, v58, v211
	v_sub_f32_e32 v59, v59, v211
	v_sub_f32_e32 v60, v60, v211
	v_sub_f32_e32 v61, v61, v211
	v_mul_f32_e32 v58, v215, v58
	v_mul_f32_e32 v59, v215, v59
	v_mul_f32_e32 v60, v215, v60
	v_mul_f32_e32 v61, v215, v61
	v_fma_f32 v58, v78, v58, v108
	v_fma_f32 v59, v79, v59, v109
	v_fma_f32 v60, v80, v60, v110
	v_fma_f32 v61, v81, v61, v111
	global_store_dwordx4 v243, v[58:61], s[26:27] offset:128
	v_sub_f32_e32 v34, v34, v211
	v_sub_f32_e32 v35, v35, v211
	v_sub_f32_e32 v36, v36, v211
	v_sub_f32_e32 v37, v37, v211
	v_mul_f32_e32 v34, v215, v34
	v_mul_f32_e32 v35, v215, v35
	v_mul_f32_e32 v36, v215, v36
	v_mul_f32_e32 v37, v215, v37
	v_fma_f32 v34, v82, v34, v172
	v_fma_f32 v35, v83, v35, v173
	v_fma_f32 v36, v84, v36, v174
	v_fma_f32 v37, v85, v37, v175
	global_store_dwordx4 v243, v[34:37], s[26:27] offset:192
	v_sub_f32_e32 v30, v30, v212
	v_sub_f32_e32 v31, v31, v212
	v_sub_f32_e32 v32, v32, v212
	v_sub_f32_e32 v33, v33, v212
	v_mul_f32_e32 v30, v216, v30
	v_mul_f32_e32 v31, v216, v31
	v_mul_f32_e32 v32, v216, v32
	v_mul_f32_e32 v33, v216, v33
	v_fma_f32 v30, v66, v30, v90
	v_fma_f32 v31, v67, v31, v91
	v_fma_f32 v32, v68, v32, v92
	v_fma_f32 v33, v69, v33, v93
	global_store_dwordx4 v244, v[30:33], s[26:27]
	v_sub_f32_e32 v26, v26, v212
	v_sub_f32_e32 v27, v27, v212
	v_sub_f32_e32 v28, v28, v212
	v_sub_f32_e32 v29, v29, v212
	v_mul_f32_e32 v26, v216, v26
	v_mul_f32_e32 v27, v216, v27
	v_mul_f32_e32 v28, v216, v28
	v_mul_f32_e32 v29, v216, v29
	v_fma_f32 v26, v74, v26, v94
	v_fma_f32 v27, v75, v27, v95
	v_fma_f32 v28, v76, v28, v96
	v_fma_f32 v29, v77, v29, v97
	global_store_dwordx4 v244, v[26:29], s[26:27] offset:64
	v_sub_f32_e32 v22, v22, v212
	v_sub_f32_e32 v23, v23, v212
	v_sub_f32_e32 v24, v24, v212
	v_sub_f32_e32 v25, v25, v212
	v_mul_f32_e32 v22, v216, v22
	v_mul_f32_e32 v23, v216, v23
	v_mul_f32_e32 v24, v216, v24
	v_mul_f32_e32 v25, v216, v25
	v_fma_f32 v22, v78, v22, v108
	v_fma_f32 v23, v79, v23, v109
	v_fma_f32 v24, v80, v24, v110
	v_fma_f32 v25, v81, v25, v111
	global_store_dwordx4 v244, v[22:25], s[26:27] offset:128
	v_sub_f32_e32 v18, v18, v212
	v_sub_f32_e32 v19, v19, v212
	v_sub_f32_e32 v20, v20, v212
	v_sub_f32_e32 v21, v21, v212
	v_mul_f32_e32 v18, v216, v18
	v_mul_f32_e32 v19, v216, v19
	v_mul_f32_e32 v20, v216, v20
	v_mul_f32_e32 v21, v216, v21
	v_fma_f32 v18, v82, v18, v172
	v_fma_f32 v19, v83, v19, v173
	v_fma_f32 v20, v84, v20, v174
	v_fma_f32 v21, v85, v21, v175
	global_store_dwordx4 v244, v[18:21], s[26:27] offset:192
	v_sub_f32_e32 v14, v14, v213
	v_sub_f32_e32 v15, v15, v213
	v_sub_f32_e32 v16, v16, v213
	v_sub_f32_e32 v17, v17, v213
	v_mul_f32_e32 v14, v217, v14
	v_mul_f32_e32 v15, v217, v15
	v_mul_f32_e32 v16, v217, v16
	v_mul_f32_e32 v17, v217, v17
	v_fma_f32 v14, v66, v14, v90
	v_fma_f32 v15, v67, v15, v91
	v_fma_f32 v16, v68, v16, v92
	v_fma_f32 v17, v69, v17, v93
	global_store_dwordx4 v245, v[14:17], s[26:27]
	v_sub_f32_e32 v10, v10, v213
	v_sub_f32_e32 v11, v11, v213
	v_sub_f32_e32 v12, v12, v213
	v_sub_f32_e32 v13, v13, v213
	v_mul_f32_e32 v10, v217, v10
	v_mul_f32_e32 v11, v217, v11
	v_mul_f32_e32 v12, v217, v12
	v_mul_f32_e32 v13, v217, v13
	v_fma_f32 v10, v74, v10, v94
	v_fma_f32 v11, v75, v11, v95
	v_fma_f32 v12, v76, v12, v96
	v_fma_f32 v13, v77, v13, v97
	global_store_dwordx4 v245, v[10:13], s[26:27] offset:64
	v_sub_f32_e32 v6, v6, v213
	v_sub_f32_e32 v7, v7, v213
	v_sub_f32_e32 v8, v8, v213
	v_sub_f32_e32 v9, v9, v213
	v_mul_f32_e32 v6, v217, v6
	v_mul_f32_e32 v7, v217, v7
	v_mul_f32_e32 v8, v217, v8
	v_mul_f32_e32 v9, v217, v9
	v_fma_f32 v6, v78, v6, v108
	v_fma_f32 v7, v79, v7, v109
	v_fma_f32 v8, v80, v8, v110
	v_fma_f32 v9, v81, v9, v111
	global_store_dwordx4 v245, v[6:9], s[26:27] offset:128
	v_sub_f32_e32 v2, v2, v213
	v_sub_f32_e32 v3, v3, v213
	v_sub_f32_e32 v4, v4, v213
	v_sub_f32_e32 v5, v5, v213
	v_mul_f32_e32 v2, v217, v2
	v_mul_f32_e32 v3, v217, v3
	v_mul_f32_e32 v4, v217, v4
	v_mul_f32_e32 v5, v217, v5
	v_fma_f32 v2, v82, v2, v172
	v_fma_f32 v3, v83, v3, v173
	v_fma_f32 v4, v84, v4, v174
	v_fma_f32 v5, v85, v5, v175
	global_store_dwordx4 v245, v[2:5], s[26:27] offset:192
	s_add_u32 s44, s94, 0x7b48000
	s_addc_u32 s45, s95, 0
	s_waitcnt vmcnt(16)
	v_add_f32_e32 v38, 1.0, v38
	v_add_f32_e32 v39, 1.0, v39
	v_add_f32_e32 v40, 1.0, v40
	v_add_f32_e32 v41, 1.0, v41
	v_add_f32_e32 v42, 1.0, v42
	v_add_f32_e32 v43, 1.0, v43
	v_add_f32_e32 v44, 1.0, v44
	v_add_f32_e32 v45, 1.0, v45
	v_add_f32_e32 v46, 1.0, v46
	v_add_f32_e32 v47, 1.0, v47
	v_add_f32_e32 v48, 1.0, v48
	v_add_f32_e32 v49, 1.0, v49
	v_add_f32_e32 v50, 1.0, v50
	v_add_f32_e32 v51, 1.0, v51
	v_add_f32_e32 v52, 1.0, v52
	v_add_f32_e32 v53, 1.0, v53
	v_lshrrev_b32_e32 v218, 1, v242
	v_lshrrev_b32_e32 v219, 1, v243
	v_lshrrev_b32_e32 v220, 1, v244
	v_lshrrev_b32_e32 v221, 1, v245
	v_fma_f32 v62, v38, v62, v226
	v_fma_f32 v63, v39, v63, v227
	v_fma_f32 v64, v40, v64, v228
	v_fma_f32 v65, v41, v65, v229
	v_cvt_pk_bf16_f32 v62, v62, v63
	v_cvt_pk_bf16_f32 v63, v64, v65
	global_store_dwordx2 v218, v[62:63], s[44:45]
	v_fma_f32 v86, v42, v86, v230
	v_fma_f32 v87, v43, v87, v231
	v_fma_f32 v88, v44, v88, v232
	v_fma_f32 v89, v45, v89, v233
	v_cvt_pk_bf16_f32 v86, v86, v87
	v_cvt_pk_bf16_f32 v87, v88, v89
	global_store_dwordx2 v218, v[86:87], s[44:45] offset:32
	v_fma_f32 v70, v46, v70, v234
	v_fma_f32 v71, v47, v71, v235
	v_fma_f32 v72, v48, v72, v236
	v_fma_f32 v73, v49, v73, v237
	v_cvt_pk_bf16_f32 v70, v70, v71
	v_cvt_pk_bf16_f32 v71, v72, v73
	global_store_dwordx2 v218, v[70:71], s[44:45] offset:64
	v_fma_f32 v176, v50, v176, v238
	v_fma_f32 v177, v51, v177, v239
	v_fma_f32 v178, v52, v178, v240
	v_fma_f32 v179, v53, v179, v241
	v_cvt_pk_bf16_f32 v176, v176, v177
	v_cvt_pk_bf16_f32 v177, v178, v179
	global_store_dwordx2 v218, v[176:177], s[44:45] offset:96
	v_fma_f32 v202, v38, v202, v226
	v_fma_f32 v203, v39, v203, v227
	v_fma_f32 v204, v40, v204, v228
	v_fma_f32 v205, v41, v205, v229
	v_cvt_pk_bf16_f32 v202, v202, v203
	v_cvt_pk_bf16_f32 v203, v204, v205
	global_store_dwordx2 v219, v[202:203], s[44:45]
	v_fma_f32 v54, v42, v54, v230
	v_fma_f32 v55, v43, v55, v231
	v_fma_f32 v56, v44, v56, v232
	v_fma_f32 v57, v45, v57, v233
	v_cvt_pk_bf16_f32 v54, v54, v55
	v_cvt_pk_bf16_f32 v55, v56, v57
	global_store_dwordx2 v219, v[54:55], s[44:45] offset:32
	v_fma_f32 v58, v46, v58, v234
	v_fma_f32 v59, v47, v59, v235
	v_fma_f32 v60, v48, v60, v236
	v_fma_f32 v61, v49, v61, v237
	v_cvt_pk_bf16_f32 v58, v58, v59
	v_cvt_pk_bf16_f32 v59, v60, v61
	global_store_dwordx2 v219, v[58:59], s[44:45] offset:64
	v_fma_f32 v34, v50, v34, v238
	v_fma_f32 v35, v51, v35, v239
	v_fma_f32 v36, v52, v36, v240
	v_fma_f32 v37, v53, v37, v241
	v_cvt_pk_bf16_f32 v34, v34, v35
	v_cvt_pk_bf16_f32 v35, v36, v37
	global_store_dwordx2 v219, v[34:35], s[44:45] offset:96
	v_fma_f32 v30, v38, v30, v226
	v_fma_f32 v31, v39, v31, v227
	v_fma_f32 v32, v40, v32, v228
	v_fma_f32 v33, v41, v33, v229
	v_cvt_pk_bf16_f32 v30, v30, v31
	v_cvt_pk_bf16_f32 v31, v32, v33
	global_store_dwordx2 v220, v[30:31], s[44:45]
	v_fma_f32 v26, v42, v26, v230
	v_fma_f32 v27, v43, v27, v231
	v_fma_f32 v28, v44, v28, v232
	v_fma_f32 v29, v45, v29, v233
	v_cvt_pk_bf16_f32 v26, v26, v27
	v_cvt_pk_bf16_f32 v27, v28, v29
	global_store_dwordx2 v220, v[26:27], s[44:45] offset:32
	v_fma_f32 v22, v46, v22, v234
	v_fma_f32 v23, v47, v23, v235
	v_fma_f32 v24, v48, v24, v236
	v_fma_f32 v25, v49, v25, v237
	v_cvt_pk_bf16_f32 v22, v22, v23
	v_cvt_pk_bf16_f32 v23, v24, v25
	global_store_dwordx2 v220, v[22:23], s[44:45] offset:64
	v_fma_f32 v18, v50, v18, v238
	v_fma_f32 v19, v51, v19, v239
	v_fma_f32 v20, v52, v20, v240
	v_fma_f32 v21, v53, v21, v241
	v_cvt_pk_bf16_f32 v18, v18, v19
	v_cvt_pk_bf16_f32 v19, v20, v21
	global_store_dwordx2 v220, v[18:19], s[44:45] offset:96
	v_fma_f32 v14, v38, v14, v226
	v_fma_f32 v15, v39, v15, v227
	v_fma_f32 v16, v40, v16, v228
	v_fma_f32 v17, v41, v17, v229
	v_cvt_pk_bf16_f32 v14, v14, v15
	v_cvt_pk_bf16_f32 v15, v16, v17
	global_store_dwordx2 v221, v[14:15], s[44:45]
	v_fma_f32 v10, v42, v10, v230
	v_fma_f32 v11, v43, v11, v231
	v_fma_f32 v12, v44, v12, v232
	v_fma_f32 v13, v45, v13, v233
	v_cvt_pk_bf16_f32 v10, v10, v11
	v_cvt_pk_bf16_f32 v11, v12, v13
	global_store_dwordx2 v221, v[10:11], s[44:45] offset:32
	v_fma_f32 v6, v46, v6, v234
	v_fma_f32 v7, v47, v7, v235
	v_fma_f32 v8, v48, v8, v236
	v_fma_f32 v9, v49, v9, v237
	v_cvt_pk_bf16_f32 v6, v6, v7
	v_cvt_pk_bf16_f32 v7, v8, v9
	global_store_dwordx2 v221, v[6:7], s[44:45] offset:64
	v_fma_f32 v2, v50, v2, v238
	v_fma_f32 v3, v51, v3, v239
	v_fma_f32 v4, v52, v4, v240
	v_fma_f32 v5, v53, v5, v241
	v_cvt_pk_bf16_f32 v2, v2, v3
	v_cvt_pk_bf16_f32 v3, v4, v5
	global_store_dwordx2 v221, v[2:3], s[44:45] offset:96
	v_readlane_b32 s78, v255, 33
	v_readlane_b32 s79, v255, 34
	s_barrier
	s_load_dword s6, s[78:79], 0x0
	s_mov_b64 s[76:77], 0x7b4c180
	s_mov_b64 s[68:69], 0x7b54180
	s_mov_b64 s[74:75], 0x68800
	s_waitcnt lgkmcnt(0)
	s_add_i32 s60, s6, s60
	s_cmpk_gt_i32 s60, 0xbf
	s_cbranch_scc0 .LBB0_93

.LBB0_413:
	s_mul_hi_u32 s27, s23, 0xaaaaaaab
	s_lshr_b32 s27, s27, 1
	s_mul_i32 s27, s27, 0x24000
	s_waitcnt lgkmcnt(0)
	v_mfma_f32_16x16x32_bf16 v[66:69], v[22:25], v[26:29], v[66:69]
	v_add_u32_e32 v222, s14, v113
	s_mul_hi_u32 s34, s19, 0xaaaaaaab
	s_lshr_b32 s34, s34, 1
	v_mfma_f32_16x16x32_bf16 v[62:65], v[18:21], v[26:29], v[62:65]
	s_mul_i32 s34, s34, 0x24000
	v_subrev_u32_e32 v182, s34, v126
	v_subrev_u32_e32 v191, s34, v127
	v_mfma_f32_16x16x32_bf16 v[58:61], v[10:13], v[26:29], v[58:61]
	v_subrev_u32_e32 v201, s34, v128
	v_mfma_f32_16x16x32_bf16 v[54:57], v[6:9], v[26:29], v[54:57]
	v_subrev_u32_e32 v26, s27, v125
	v_mfma_f32_16x16x32_bf16 v[50:53], v[22:25], v[14:17], v[50:53]
	v_mfma_f32_16x16x32_bf16 v[46:49], v[18:21], v[14:17], v[46:49]
	v_mfma_f32_16x16x32_bf16 v[42:45], v[10:13], v[14:17], v[42:45]
	v_mfma_f32_16x16x32_bf16 v[38:41], v[6:9], v[14:17], v[38:41]
	v_subrev_u32_e32 v14, s27, v129
	v_add_u32_e32 v16, v222, v26
	v_add_u32_e32 v14, v222, v14
	v_mfma_f32_16x16x32_bf16 v[34:37], v[22:25], v[30:33], v[34:37]
	v_subrev_u32_e32 v15, s34, v130
	v_mfma_f32_16x16x32_bf16 v[86:89], v[22:25], v[2:5], v[86:89]
	ds_read_b128 v[22:25], v16
	ds_read_b128 v[174:177], v16 offset:2048
	ds_read_b128 v[178:181], v16 offset:4096
	ds_read_b128 v[202:205], v16 offset:6144
	ds_read_b128 v[206:209], v14 offset:32768
	ds_read_b128 v[210:213], v14 offset:34816
	ds_read_b128 v[214:217], v14 offset:36864
	ds_read_b128 v[218:221], v14 offset:38912
	v_mfma_f32_16x16x32_bf16 v[74:77], v[18:21], v[30:33], v[74:77]
	v_mfma_f32_16x16x32_bf16 v[70:73], v[10:13], v[30:33], v[70:73]
	v_mfma_f32_16x16x32_bf16 v[78:81], v[6:9], v[30:33], v[78:81]
	v_mfma_f32_16x16x32_bf16 v[94:97], v[18:21], v[2:5], v[94:97]
	v_mfma_f32_16x16x32_bf16 v[90:93], v[10:13], v[2:5], v[90:93]
	v_mfma_f32_16x16x32_bf16 v[82:85], v[6:9], v[2:5], v[82:85]
	s_add_i32 s27, s13, 4
	s_mul_i32 s34, s27, 0xab
	s_bfe_u32 s34, s34, 0x70009
	s_mul_i32 s34, s34, 3
	s_sub_i32 s27, s27, s34
	s_and_b32 s27, s27, 0xff
	s_mul_i32 s27, s27, 0xc000
	s_waitcnt vmcnt(6)
	v_add_u32_e32 v2, v222, v15
	v_add_u32_e32 v6, v222, v201
	s_waitcnt lgkmcnt(0)
	v_mfma_f32_16x16x32_bf16 v[66:69], v[206:209], v[174:177], v[66:69]
	s_mov_b64 s[36:37], 0xe1d8180
	s_add_i32 s34, s27, s8
	s_waitcnt lgkmcnt(0)
	v_mfma_f32_16x16x32_bf16 v[62:65], v[210:213], v[174:177], v[62:65]
	s_barrier
	ds_read_b128 v[30:33], v2
	ds_read_b128 v[26:29], v2 offset:2048
	ds_read_b128 v[14:17], v2 offset:4096
	ds_read_b128 v[2:5], v2 offset:6144
	v_mfma_f32_16x16x32_bf16 v[58:61], v[214:217], v[174:177], v[58:61]
	v_add_u32_e32 v7, v222, v191
	s_mov_b32 m0, s34
	s_add_i32 s27, s27, s9
	v_mfma_f32_16x16x32_bf16 v[54:57], v[218:221], v[174:177], v[54:57]
	v_lshl_add_u64 v[174:175], v[108:109], 0, v[98:99]
	v_lshl_add_u64 v[176:177], v[174:175], 0, s[36:37]
	s_mov_b64 s[36:37], 0xe1e8180
	v_mfma_f32_16x16x32_bf16 v[34:37], v[206:209], v[22:25], v[34:37]
	s_add_i32 s23, s23, 1
	v_mfma_f32_16x16x32_bf16 v[74:77], v[210:213], v[22:25], v[74:77]
	v_mfma_f32_16x16x32_bf16 v[70:73], v[214:217], v[22:25], v[70:73]
	v_mfma_f32_16x16x32_bf16 v[78:81], v[218:221], v[22:25], v[78:81]
	ds_read_b128 v[22:25], v6
	ds_read_b128 v[18:21], v7
	v_add_u32_e32 v6, v222, v182
	ds_read_b128 v[10:13], v6
	ds_read_b128 v[6:9], v6 offset:2048
	global_load_lds_dwordx4 v[176:177], off
	v_lshl_add_u64 v[176:177], v[174:175], 0, s[36:37]
	s_add_i32 m0, s34, 0x400
	s_mov_b64 s[36:37], 0xe1f8180
	global_load_lds_dwordx4 v[176:177], off
	v_lshl_add_u64 v[176:177], v[174:175], 0, s[36:37]
	s_add_i32 m0, s34, 0x800
	s_mov_b64 s[36:37], 0xe208180
	global_load_lds_dwordx4 v[176:177], off
	v_lshl_add_u64 v[174:175], v[174:175], 0, s[36:37]
	s_add_i32 m0, s34, 0xc00
	s_mov_b64 s[36:37], 0x4300180
	global_load_lds_dwordx4 v[174:175], off
	v_lshl_add_u64 v[174:175], v[110:111], 0, v[98:99]
	v_lshl_add_u64 v[176:177], v[174:175], 0, s[36:37]
	s_add_i32 m0, s27, 0x8000
	s_mov_b64 s[36:37], 0x4310180
	global_load_lds_dwordx4 v[176:177], off
	v_lshl_add_u64 v[174:175], v[174:175], 0, s[36:37]
	s_add_i32 m0, s27, 0x8400
	v_mfma_f32_16x16x32_bf16 v[50:53], v[206:209], v[178:181], v[50:53]
	global_load_lds_dwordx4 v[174:175], off
	v_mfma_f32_16x16x32_bf16 v[46:49], v[210:213], v[178:181], v[46:49]
	v_mfma_f32_16x16x32_bf16 v[42:45], v[214:217], v[178:181], v[42:45]
	v_mfma_f32_16x16x32_bf16 v[38:41], v[218:221], v[178:181], v[38:41]
	v_mfma_f32_16x16x32_bf16 v[86:89], v[206:209], v[202:205], v[86:89]
	v_mfma_f32_16x16x32_bf16 v[94:97], v[210:213], v[202:205], v[94:97]
	v_mfma_f32_16x16x32_bf16 v[90:93], v[214:217], v[202:205], v[90:93]
	v_mfma_f32_16x16x32_bf16 v[82:85], v[218:221], v[202:205], v[82:85]
	s_add_i32 s13, s13, 1
	s_add_i32 s14, s14, 0xc000
	s_add_i32 s19, s19, 1
	v_lshl_add_u64 v[108:109], v[108:109], 0, s[2:3]
	s_cmp_eq_u32 s14, 0x2dc000
	v_lshl_add_u64 v[110:111], v[110:111], 0, s[2:3]
	s_cbranch_scc0 .LBB0_413
	s_waitcnt lgkmcnt(0)
	v_mfma_f32_16x16x32_bf16 v[34:37], v[22:25], v[30:33], v[34:37]
	v_mfma_f32_16x16x32_bf16 v[74:77], v[18:21], v[30:33], v[74:77]
	v_mfma_f32_16x16x32_bf16 v[70:73], v[10:13], v[30:33], v[70:73]
	v_mfma_f32_16x16x32_bf16 v[30:33], v[6:9], v[30:33], v[78:81]
	v_mfma_f32_16x16x32_bf16 v[66:69], v[22:25], v[26:29], v[66:69]
	v_mfma_f32_16x16x32_bf16 v[62:65], v[18:21], v[26:29], v[62:65]
	v_mfma_f32_16x16x32_bf16 v[58:61], v[10:13], v[26:29], v[58:61]
	v_mfma_f32_16x16x32_bf16 v[26:29], v[6:9], v[26:29], v[54:57]
	v_mfma_f32_16x16x32_bf16 v[50:53], v[22:25], v[14:17], v[50:53]
	v_mfma_f32_16x16x32_bf16 v[46:49], v[18:21], v[14:17], v[46:49]
	v_mfma_f32_16x16x32_bf16 v[42:45], v[10:13], v[14:17], v[42:45]
	v_mfma_f32_16x16x32_bf16 v[14:17], v[6:9], v[14:17], v[38:41]
	v_mfma_f32_16x16x32_bf16 v[22:25], v[22:25], v[2:5], v[86:89]
	s_nop 1
	ds_read_b128 v[38:41], v131
	ds_read_b128 v[54:57], v132 offset:2048
	ds_read_b128 v[78:81], v132 offset:4096
	ds_read_b128 v[86:89], v132 offset:6144
	v_mfma_f32_16x16x32_bf16 v[18:21], v[18:21], v[2:5], v[94:97]
	v_mfma_f32_16x16x32_bf16 v[10:13], v[10:13], v[2:5], v[90:93]
	s_nop 2
	ds_read_b128 v[90:93], v133 offset:32768
	ds_read_b128 v[94:97], v134 offset:34816
	ds_read_b128 v[108:111], v134 offset:36864
	ds_read_b128 v[174:177], v134 offset:38912
	v_mfma_f32_16x16x32_bf16 v[2:5], v[6:9], v[2:5], v[82:85]
	s_waitcnt lgkmcnt(0)
	v_mfma_f32_16x16x32_bf16 v[6:9], v[90:93], v[38:41], v[34:37]
	s_waitcnt vmcnt(6)
	s_waitcnt lgkmcnt(0)
	s_barrier
	v_mfma_f32_16x16x32_bf16 v[34:37], v[94:97], v[38:41], v[74:77]
	v_mfma_f32_16x16x32_bf16 v[70:73], v[108:111], v[38:41], v[70:73]
	v_mfma_f32_16x16x32_bf16 v[30:33], v[174:177], v[38:41], v[30:33]
	v_mfma_f32_16x16x32_bf16 v[38:41], v[90:93], v[54:57], v[66:69]
	v_mfma_f32_16x16x32_bf16 v[62:65], v[94:97], v[54:57], v[62:65]
	v_mfma_f32_16x16x32_bf16 v[58:61], v[108:111], v[54:57], v[58:61]
	v_mfma_f32_16x16x32_bf16 v[26:29], v[174:177], v[54:57], v[26:29]
	v_add_u32_e32 v54, v124, v115
	ds_read_b128 v[54:57], v54
	ds_read_b128 v[66:69], v135 offset:2048
	v_mfma_f32_16x16x32_bf16 v[50:53], v[90:93], v[78:81], v[50:53]
	v_mfma_f32_16x16x32_bf16 v[46:49], v[94:97], v[78:81], v[46:49]
	v_mfma_f32_16x16x32_bf16 v[42:45], v[108:111], v[78:81], v[42:45]
	v_mfma_f32_16x16x32_bf16 v[22:25], v[90:93], v[86:89], v[22:25]
	v_add_u32_e32 v90, 0x20800, v164
	v_mfma_f32_16x16x32_bf16 v[18:21], v[94:97], v[86:89], v[18:21]
	v_add_u32_e32 v94, 0x21000, v164
	v_mfma_f32_16x16x32_bf16 v[10:13], v[108:111], v[86:89], v[10:13]
	v_add_u32_e32 v108, 0x21800, v164
	v_mfma_f32_16x16x32_bf16 v[14:17], v[174:177], v[78:81], v[14:17]
	ds_read_b128 v[74:77], v135 offset:4096
	ds_read_b128 v[78:81], v135 offset:6144
	ds_read_b128 v[82:85], v163
	ds_read_b128 v[90:93], v90
	ds_read_b128 v[94:97], v94
	ds_read_b128 v[108:111], v108
	v_mfma_f32_16x16x32_bf16 v[2:5], v[174:177], v[86:89], v[2:5]
	s_waitcnt lgkmcnt(0)
	v_mfma_f32_16x16x32_bf16 v[6:9], v[82:85], v[54:57], v[6:9]
	v_mfma_f32_16x16x32_bf16 v[34:37], v[90:93], v[54:57], v[34:37]
	v_mfma_f32_16x16x32_bf16 v[70:73], v[94:97], v[54:57], v[70:73]
	v_mfma_f32_16x16x32_bf16 v[30:33], v[108:111], v[54:57], v[30:33]
	v_mfma_f32_16x16x32_bf16 v[54:57], v[90:93], v[66:69], v[62:65]
	s_nop 2
	v_add_u32_e32 v62, v124, v119
	v_mfma_f32_16x16x32_bf16 v[38:41], v[82:85], v[66:69], v[38:41]
	v_mfma_f32_16x16x32_bf16 v[58:61], v[94:97], v[66:69], v[58:61]
	v_mfma_f32_16x16x32_bf16 v[26:29], v[108:111], v[66:69], v[26:29]
	v_mfma_f32_16x16x32_bf16 v[50:53], v[82:85], v[74:77], v[50:53]
	v_mfma_f32_16x16x32_bf16 v[46:49], v[90:93], v[74:77], v[46:49]
	v_mfma_f32_16x16x32_bf16 v[42:45], v[94:97], v[74:77], v[42:45]
	v_mfma_f32_16x16x32_bf16 v[14:17], v[108:111], v[74:77], v[14:17]
	v_mfma_f32_16x16x32_bf16 v[22:25], v[82:85], v[78:81], v[22:25]
	ds_read_b128 v[62:65], v62
	ds_read_b128 v[66:69], v165
	ds_read_b128 v[74:77], v166
	ds_read_b128 v[82:85], v167
	v_mfma_f32_16x16x32_bf16 v[18:21], v[90:93], v[78:81], v[18:21]
	v_mfma_f32_16x16x32_bf16 v[10:13], v[94:97], v[78:81], v[10:13]
	ds_read_b128 v[86:89], v168
	ds_read_b128 v[90:93], v169
	ds_read_b128 v[94:97], v170
	ds_read_b128 v[174:177], v171
	v_mfma_f32_16x16x32_bf16 v[2:5], v[108:111], v[78:81], v[2:5]
	s_waitcnt vmcnt(0)
	s_waitcnt lgkmcnt(0)
	v_mfma_f32_16x16x32_bf16 v[6:9], v[86:89], v[62:65], v[6:9]
	s_waitcnt lgkmcnt(0)
	s_barrier
	v_mfma_f32_16x16x32_bf16 v[34:37], v[90:93], v[62:65], v[34:37]
	v_mfma_f32_16x16x32_bf16 v[70:73], v[94:97], v[62:65], v[70:73]
	v_mfma_f32_16x16x32_bf16 v[30:33], v[174:177], v[62:65], v[30:33]
	v_mfma_f32_16x16x32_bf16 v[38:41], v[86:89], v[66:69], v[38:41]
	v_mfma_f32_16x16x32_bf16 v[54:57], v[90:93], v[66:69], v[54:57]
	v_mfma_f32_16x16x32_bf16 v[58:61], v[94:97], v[66:69], v[58:61]
	v_mfma_f32_16x16x32_bf16 v[26:29], v[174:177], v[66:69], v[26:29]
	v_mfma_f32_16x16x32_bf16 v[50:53], v[86:89], v[74:77], v[50:53]
	v_mfma_f32_16x16x32_bf16 v[46:49], v[90:93], v[74:77], v[46:49]
	v_mfma_f32_16x16x32_bf16 v[42:45], v[94:97], v[74:77], v[42:45]
	v_mfma_f32_16x16x32_bf16 v[14:17], v[174:177], v[74:77], v[14:17]
	ds_read_b128 v[62:65], v164 offset:38912
	ds_read_b128 v[66:69], v164 offset:36864
	ds_read_b128 v[74:77], v164 offset:34816
	ds_read_b128 v[78:81], v161 offset:32768
	v_mfma_f32_16x16x32_bf16 v[22:25], v[86:89], v[82:85], v[22:25]
	v_mfma_f32_16x16x32_bf16 v[18:21], v[90:93], v[82:85], v[18:21]
	v_mfma_f32_16x16x32_bf16 v[10:13], v[94:97], v[82:85], v[10:13]
	ds_read_b128 v[86:89], v173 offset:6144
	ds_read_b128 v[90:93], v173 offset:4096
	ds_read_b128 v[94:97], v173 offset:2048
	ds_read_b128 v[108:111], v172
	v_mfma_f32_16x16x32_bf16 v[2:5], v[174:177], v[82:85], v[2:5]
	s_waitcnt lgkmcnt(0)
	v_mfma_f32_16x16x32_bf16 v[38:41], v[78:81], v[94:97], v[38:41]
	v_add_u32_e32 v82, v114, v119
	v_add_u32_e32 v172, v118, v119
	v_mfma_f32_16x16x32_bf16 v[54:57], v[74:77], v[94:97], v[54:57]
	v_mfma_f32_16x16x32_bf16 v[58:61], v[66:69], v[94:97], v[58:61]
	v_mfma_f32_16x16x32_bf16 v[26:29], v[62:65], v[94:97], v[26:29]
	v_add_u32_e32 v94, v117, v119
	v_mfma_f32_16x16x32_bf16 v[50:53], v[78:81], v[90:93], v[50:53]
	v_mfma_f32_16x16x32_bf16 v[46:49], v[74:77], v[90:93], v[46:49]
	v_mfma_f32_16x16x32_bf16 v[42:45], v[66:69], v[90:93], v[42:45]
	v_mfma_f32_16x16x32_bf16 v[14:17], v[62:65], v[90:93], v[14:17]
	v_add_u32_e32 v90, v116, v119
	v_mfma_f32_16x16x32_bf16 v[6:9], v[78:81], v[108:111], v[6:9]
	v_mfma_f32_16x16x32_bf16 v[34:37], v[74:77], v[108:111], v[34:37]
	v_mfma_f32_16x16x32_bf16 v[70:73], v[66:69], v[108:111], v[70:73]
	v_mfma_f32_16x16x32_bf16 v[30:33], v[62:65], v[108:111], v[30:33]
	v_mfma_f32_16x16x32_bf16 v[78:81], v[78:81], v[86:89], v[22:25]
	s_nop 2
	ds_read_b128 v[22:25], v82
	ds_read_b128 v[82:85], v90 offset:2048
	v_mfma_f32_16x16x32_bf16 v[74:77], v[74:77], v[86:89], v[18:21]
	s_nop 2
	ds_read_b128 v[18:21], v90 offset:4096
	ds_read_b128 v[90:93], v90 offset:6144
	v_mfma_f32_16x16x32_bf16 v[66:69], v[66:69], v[86:89], v[10:13]
	s_nop 2
	ds_read_b128 v[10:13], v94 offset:32768
	ds_read_b128 v[94:97], v172 offset:34816
	ds_read_b128 v[108:111], v172 offset:36864
	ds_read_b128 v[172:175], v172 offset:38912
	v_mfma_f32_16x16x32_bf16 v[2:5], v[62:65], v[86:89], v[2:5]
	s_waitcnt vmcnt(0)
	s_waitcnt lgkmcnt(0)
	v_mfma_f32_16x16x32_bf16 v[2:5], v[172:175], v[90:93], v[2:5]
	s_waitcnt lgkmcnt(0)
	s_barrier
	v_mfma_f32_16x16x32_bf16 v[62:65], v[10:13], v[22:25], v[6:9]
	v_mfma_f32_16x16x32_bf16 v[86:89], v[94:97], v[22:25], v[34:37]
	v_mfma_f32_16x16x32_bf16 v[70:73], v[108:111], v[22:25], v[70:73]
	v_mfma_f32_16x16x32_bf16 v[176:179], v[172:175], v[22:25], v[30:33]
	v_mfma_f32_16x16x32_bf16 v[202:205], v[10:13], v[82:85], v[38:41]
	v_mfma_f32_16x16x32_bf16 v[54:57], v[94:97], v[82:85], v[54:57]
	v_mfma_f32_16x16x32_bf16 v[58:61], v[108:111], v[82:85], v[58:61]
	v_mfma_f32_16x16x32_bf16 v[34:37], v[172:175], v[82:85], v[26:29]
	v_mfma_f32_16x16x32_bf16 v[30:33], v[10:13], v[18:21], v[50:53]
	v_mfma_f32_16x16x32_bf16 v[26:29], v[94:97], v[18:21], v[46:49]
	v_mfma_f32_16x16x32_bf16 v[22:25], v[108:111], v[18:21], v[42:45]
	v_mfma_f32_16x16x32_bf16 v[18:21], v[172:175], v[18:21], v[14:17]
	v_mfma_f32_16x16x32_bf16 v[14:17], v[10:13], v[90:93], v[78:81]
	v_mfma_f32_16x16x32_bf16 v[10:13], v[94:97], v[90:93], v[74:77]
	v_mfma_f32_16x16x32_bf16 v[6:9], v[108:111], v[90:93], v[66:69]
	s_mul_hi_i32 s54, s70, 0x2aaaaaab
	s_lshr_b32 s55, s54, 31
	s_ashr_i32 s54, s54, 2
	s_add_i32 s13, s54, s55
	s_mul_i32 s54, s13, 24
	s_sub_i32 s14, s70, s54
	v_readfirstlane_b32 s54, v137
	s_lshr_b32 s54, s54, 6
	s_and_b32 s19, s54, 1
	s_lshr_b32 s54, s54, 1
	s_lshl_b32 s54, s54, 6
	s_lshl_b32 s50, s14, 8
	s_add_i32 s50, s50, s54
	s_lshl_b32 s51, s13, 7
	s_lshl_b32 s54, s19, 6
	s_add_i32 s51, s51, s54
	s_add_i32 s54, s50, 0xfffff000
	s_ashr_i32 s54, s54, 10
	s_add_i32 s54, s54, 1
	s_cmpk_lt_i32 s50, 0x1000
	s_cselect_b32 s52, 0, s54
	v_readlane_b32 s53, v255, 40
	v_and_b32_e32 v250, 63, v137
	v_and_b32_e32 v251, 15, v250
	v_lshrrev_b32_e32 v252, 4, v250
	s_mul_i32 s54, s53, 3
	s_add_i32 s54, s54, s52
	s_mul_i32 s54, s54, 0x6000
	s_add_u32 s22, s94, 0x6300000
	s_addc_u32 s23, s95, 0
	s_add_u32 s22, s22, s54
	s_addc_u32 s23, s23, 0
	s_add_u32 s26, s94, 0x6348000
	s_addc_u32 s27, s95, 0
	v_add_u32_e32 v242, s50, v251
	v_lshlrev_b32_e32 v242, 12, v242
	s_lshl_b32 s54, s51, 2
	v_lshl_add_u32 v242, v252, 4, v242
	v_add_u32_e32 v242, s54, v242
	s_add_i32 s55, s51, 5120
	s_lshl_b32 s55, s55, 2
	v_lshl_add_u32 v246, v252, 4, s55
	v_add_u32_e32 v243, 0x10000, v242
	v_add_u32_e32 v244, 0x20000, v242
	v_add_u32_e32 v245, 0x30000, v242
	global_load_dwordx4 v[226:229], v246, s[22:23]
	global_load_dwordx4 v[230:233], v246, s[22:23] offset:64
	global_load_dwordx4 v[234:237], v246, s[22:23] offset:128
	global_load_dwordx4 v[238:241], v246, s[22:23] offset:192
	global_load_dwordx4 v[38:41], v242, s[26:27]
	global_load_dwordx4 v[42:45], v242, s[26:27] offset:64
	global_load_dwordx4 v[46:49], v242, s[26:27] offset:128
	global_load_dwordx4 v[50:53], v242, s[26:27] offset:192
	global_load_dwordx4 v[66:69], v243, s[26:27]
	global_load_dwordx4 v[74:77], v243, s[26:27] offset:64
	global_load_dwordx4 v[78:81], v243, s[26:27] offset:128
	global_load_dwordx4 v[82:85], v243, s[26:27] offset:192
	global_load_dwordx4 v[90:93], v244, s[26:27]
	global_load_dwordx4 v[94:97], v244, s[26:27] offset:64
	global_load_dwordx4 v[108:111], v244, s[26:27] offset:128
	global_load_dwordx4 v[172:175], v244, s[26:27] offset:192
	global_load_dwordx4 v[206:209], v245, s[26:27]
	global_load_dwordx4 v[210:213], v245, s[26:27] offset:64
	global_load_dwordx4 v[214:217], v245, s[26:27] offset:128
	global_load_dwordx4 v[218:221], v245, s[26:27] offset:192
	v_mov_b32_e32 v248, 0x3fd744fd
	v_mov_b32_e32 v249, 0x3fd744fd
	s_waitcnt vmcnt(12)
	v_pk_mul_f32 v[38:39], v[38:39], v[248:249]
	v_pk_mul_f32 v[40:41], v[40:41], v[248:249]
	v_pk_fma_f32 v[62:63], v[62:63], v[226:227], v[38:39]
	v_pk_fma_f32 v[64:65], v[64:65], v[228:229], v[40:41]
	v_pk_mul_f32 v[42:43], v[42:43], v[248:249]
	v_pk_mul_f32 v[44:45], v[44:45], v[248:249]
	v_pk_fma_f32 v[86:87], v[86:87], v[230:231], v[42:43]
	v_pk_fma_f32 v[88:89], v[88:89], v[232:233], v[44:45]
	v_pk_mul_f32 v[46:47], v[46:47], v[248:249]
	v_pk_mul_f32 v[48:49], v[48:49], v[248:249]
	v_pk_fma_f32 v[70:71], v[70:71], v[234:235], v[46:47]
	v_pk_fma_f32 v[72:73], v[72:73], v[236:237], v[48:49]
	v_pk_mul_f32 v[50:51], v[50:51], v[248:249]
	v_pk_mul_f32 v[52:53], v[52:53], v[248:249]
	v_pk_fma_f32 v[176:177], v[176:177], v[238:239], v[50:51]
	v_pk_fma_f32 v[178:179], v[178:179], v[240:241], v[52:53]
	s_waitcnt vmcnt(8)
	v_pk_mul_f32 v[66:67], v[66:67], v[248:249]
	v_pk_mul_f32 v[68:69], v[68:69], v[248:249]
	v_pk_fma_f32 v[202:203], v[202:203], v[226:227], v[66:67]
	v_pk_fma_f32 v[204:205], v[204:205], v[228:229], v[68:69]
	v_pk_mul_f32 v[74:75], v[74:75], v[248:249]
	v_pk_mul_f32 v[76:77], v[76:77], v[248:249]
	v_pk_fma_f32 v[54:55], v[54:55], v[230:231], v[74:75]
	v_pk_fma_f32 v[56:57], v[56:57], v[232:233], v[76:77]
	v_pk_mul_f32 v[78:79], v[78:79], v[248:249]
	v_pk_mul_f32 v[80:81], v[80:81], v[248:249]
	v_pk_fma_f32 v[58:59], v[58:59], v[234:235], v[78:79]
	v_pk_fma_f32 v[60:61], v[60:61], v[236:237], v[80:81]
	v_pk_mul_f32 v[82:83], v[82:83], v[248:249]
	v_pk_mul_f32 v[84:85], v[84:85], v[248:249]
	v_pk_fma_f32 v[34:35], v[34:35], v[238:239], v[82:83]
	v_pk_fma_f32 v[36:37], v[36:37], v[240:241], v[84:85]
	s_waitcnt vmcnt(4)
	v_pk_mul_f32 v[90:91], v[90:91], v[248:249]
	v_pk_mul_f32 v[92:93], v[92:93], v[248:249]
	v_pk_fma_f32 v[30:31], v[30:31], v[226:227], v[90:91]
	v_pk_fma_f32 v[32:33], v[32:33], v[228:229], v[92:93]
	v_pk_mul_f32 v[94:95], v[94:95], v[248:249]
	v_pk_mul_f32 v[96:97], v[96:97], v[248:249]
	v_pk_fma_f32 v[26:27], v[26:27], v[230:231], v[94:95]
	v_pk_fma_f32 v[28:29], v[28:29], v[232:233], v[96:97]
	v_pk_mul_f32 v[108:109], v[108:109], v[248:249]
	v_pk_mul_f32 v[110:111], v[110:111], v[248:249]
	v_pk_fma_f32 v[22:23], v[22:23], v[234:235], v[108:109]
	v_pk_fma_f32 v[24:25], v[24:25], v[236:237], v[110:111]
	v_pk_mul_f32 v[172:173], v[172:173], v[248:249]
	v_pk_mul_f32 v[174:175], v[174:175], v[248:249]
	v_pk_fma_f32 v[18:19], v[18:19], v[238:239], v[172:173]
	v_pk_fma_f32 v[20:21], v[20:21], v[240:241], v[174:175]
	s_waitcnt vmcnt(0)
	v_pk_mul_f32 v[206:207], v[206:207], v[248:249]
	v_pk_mul_f32 v[208:209], v[208:209], v[248:249]
	v_pk_fma_f32 v[14:15], v[14:15], v[226:227], v[206:207]
	v_pk_fma_f32 v[16:17], v[16:17], v[228:229], v[208:209]
	v_pk_mul_f32 v[210:211], v[210:211], v[248:249]
	v_pk_mul_f32 v[212:213], v[212:213], v[248:249]
	v_pk_fma_f32 v[10:11], v[10:11], v[230:231], v[210:211]
	v_pk_fma_f32 v[12:13], v[12:13], v[232:233], v[212:213]
	v_pk_mul_f32 v[214:215], v[214:215], v[248:249]
	v_pk_mul_f32 v[216:217], v[216:217], v[248:249]
	v_pk_fma_f32 v[6:7], v[6:7], v[234:235], v[214:215]
	v_pk_fma_f32 v[8:9], v[8:9], v[236:237], v[216:217]
	v_pk_mul_f32 v[218:219], v[218:219], v[248:249]
	v_pk_mul_f32 v[220:221], v[220:221], v[248:249]
	v_pk_fma_f32 v[2:3], v[2:3], v[238:239], v[218:219]
	v_pk_fma_f32 v[4:5], v[4:5], v[240:241], v[220:221]
	v_pk_mul_f32 v[208:209], v[62:63], v[62:63]
	v_pk_add_f32 v[206:207], v[62:63], v[64:65]
	v_pk_fma_f32 v[208:209], v[64:65], v[64:65], v[208:209]
	v_pk_add_f32 v[206:207], v[206:207], v[86:87]
	v_pk_fma_f32 v[208:209], v[86:87], v[86:87], v[208:209]
	v_pk_add_f32 v[206:207], v[206:207], v[88:89]
	v_pk_fma_f32 v[208:209], v[88:89], v[88:89], v[208:209]
	v_pk_add_f32 v[206:207], v[206:207], v[70:71]
	v_pk_fma_f32 v[208:209], v[70:71], v[70:71], v[208:209]
	v_pk_add_f32 v[206:207], v[206:207], v[72:73]
	v_pk_fma_f32 v[208:209], v[72:73], v[72:73], v[208:209]
	v_pk_add_f32 v[206:207], v[206:207], v[176:177]
	v_pk_fma_f32 v[208:209], v[176:177], v[176:177], v[208:209]
	v_pk_add_f32 v[206:207], v[206:207], v[178:179]
	v_pk_fma_f32 v[208:209], v[178:179], v[178:179], v[208:209]
	v_add_f32_e32 v206, v206, v207
	v_add_f32_e32 v208, v208, v209
	v_pk_mul_f32 v[212:213], v[202:203], v[202:203]
	v_pk_add_f32 v[210:211], v[202:203], v[204:205]
	v_pk_fma_f32 v[212:213], v[204:205], v[204:205], v[212:213]
	v_pk_add_f32 v[210:211], v[210:211], v[54:55]
	v_pk_fma_f32 v[212:213], v[54:55], v[54:55], v[212:213]
	v_pk_add_f32 v[210:211], v[210:211], v[56:57]
	v_pk_fma_f32 v[212:213], v[56:57], v[56:57], v[212:213]
	v_pk_add_f32 v[210:211], v[210:211], v[58:59]
	v_pk_fma_f32 v[212:213], v[58:59], v[58:59], v[212:213]
	v_pk_add_f32 v[210:211], v[210:211], v[60:61]
	v_pk_fma_f32 v[212:213], v[60:61], v[60:61], v[212:213]
	v_pk_add_f32 v[210:211], v[210:211], v[34:35]
	v_pk_fma_f32 v[212:213], v[34:35], v[34:35], v[212:213]
	v_pk_add_f32 v[210:211], v[210:211], v[36:37]
	v_pk_fma_f32 v[212:213], v[36:37], v[36:37], v[212:213]
	v_add_f32_e32 v210, v210, v211
	v_add_f32_e32 v212, v212, v213
	v_pk_mul_f32 v[216:217], v[30:31], v[30:31]
	v_pk_add_f32 v[214:215], v[30:31], v[32:33]
	v_pk_fma_f32 v[216:217], v[32:33], v[32:33], v[216:217]
	v_pk_add_f32 v[214:215], v[214:215], v[26:27]
	v_pk_fma_f32 v[216:217], v[26:27], v[26:27], v[216:217]
	v_pk_add_f32 v[214:215], v[214:215], v[28:29]
	v_pk_fma_f32 v[216:217], v[28:29], v[28:29], v[216:217]
	v_pk_add_f32 v[214:215], v[214:215], v[22:23]
	v_pk_fma_f32 v[216:217], v[22:23], v[22:23], v[216:217]
	v_pk_add_f32 v[214:215], v[214:215], v[24:25]
	v_pk_fma_f32 v[216:217], v[24:25], v[24:25], v[216:217]
	v_pk_add_f32 v[214:215], v[214:215], v[18:19]
	v_pk_fma_f32 v[216:217], v[18:19], v[18:19], v[216:217]
	v_pk_add_f32 v[214:215], v[214:215], v[20:21]
	v_pk_fma_f32 v[216:217], v[20:21], v[20:21], v[216:217]
	v_add_f32_e32 v214, v214, v215
	v_add_f32_e32 v216, v216, v217
	v_pk_mul_f32 v[220:221], v[14:15], v[14:15]
	v_pk_add_f32 v[218:219], v[14:15], v[16:17]
	v_pk_fma_f32 v[220:221], v[16:17], v[16:17], v[220:221]
	v_pk_add_f32 v[218:219], v[218:219], v[10:11]
	v_pk_fma_f32 v[220:221], v[10:11], v[10:11], v[220:221]
	v_pk_add_f32 v[218:219], v[218:219], v[12:13]
	v_pk_fma_f32 v[220:221], v[12:13], v[12:13], v[220:221]
	v_pk_add_f32 v[218:219], v[218:219], v[6:7]
	v_pk_fma_f32 v[220:221], v[6:7], v[6:7], v[220:221]
	v_pk_add_f32 v[218:219], v[218:219], v[8:9]
	v_pk_fma_f32 v[220:221], v[8:9], v[8:9], v[220:221]
	v_pk_add_f32 v[218:219], v[218:219], v[2:3]
	v_pk_fma_f32 v[220:221], v[2:3], v[2:3], v[220:221]
	v_pk_add_f32 v[218:219], v[218:219], v[4:5]
	v_pk_fma_f32 v[220:221], v[4:5], v[4:5], v[220:221]
	v_add_f32_e32 v218, v218, v219
	v_add_f32_e32 v220, v220, v221
	s_nop 1
	v_permlane16_swap_b32_e32 v206, v210
	v_permlane16_swap_b32_e32 v214, v218
	v_permlane16_swap_b32_e32 v208, v212
	v_permlane16_swap_b32_e32 v216, v220
	v_add_f32_e32 v206, v206, v210
	v_add_f32_e32 v214, v214, v218
	v_add_f32_e32 v208, v208, v212
	v_add_f32_e32 v216, v216, v220
	s_nop 1
	v_permlane32_swap_b32_e32 v206, v214
	v_permlane32_swap_b32_e32 v208, v216
	v_add_f32_e32 v248, v206, v214
	v_add_f32_e32 v249, v208, v216
	s_add_u32 s34, s94, 0x11e5e100
	s_addc_u32 s35, s95, 0
	v_add_u32_e32 v247, s50, v250
	v_lshlrev_b32_e32 v247, 3, v247
	s_lshl_b32 s54, s13, 1
	s_add_i32 s54, s54, s19
	s_mul_i32 s54, s54, 0xc000
	v_add_u32_e32 v246, s54, v247
	global_store_dwordx2 v246, v[248:249], s[34:35] sc1
	v_readlane_b32 s36, v253, 15
	v_readlane_b32 s37, v253, 16
	v_readlane_b32 s48, v253, 17
	v_readlane_b32 s49, v253, 18
	s_lshl_b32 s54, s53, 10
	s_add_i32 s54, s54, s51
	s_lshl_b32 s54, s54, 2
	v_lshl_add_u32 v222, v252, 4, s54
	s_nop 3
	global_load_dwordx4 v[66:69], v222, s[36:37]
	global_load_dwordx4 v[74:77], v222, s[36:37] offset:64
	global_load_dwordx4 v[78:81], v222, s[36:37] offset:128
	global_load_dwordx4 v[82:85], v222, s[36:37] offset:192
	global_load_dwordx4 v[90:93], v222, s[48:49]
	global_load_dwordx4 v[94:97], v222, s[48:49] offset:64
	global_load_dwordx4 v[108:111], v222, s[48:49] offset:128
	global_load_dwordx4 v[172:175], v222, s[48:49] offset:192
	s_waitcnt vmcnt(8)
	s_barrier
	v_cmp_eq_u32_e64 s[36:37], 0, v137
	s_nop 3
	s_and_saveexec_b64 s[48:49], s[36:37]
	s_cbranch_execz .Lln2_xdone
	s_mul_i32 s54, s53, 384
	s_lshl_b32 s55, s14, 2
	s_add_i32 s54, s54, s55
	s_add_i32 s54, s54, 192
	s_add_u32 s36, s94, 0x11e5d700
	s_addc_u32 s37, s95, 0
	s_add_u32 s36, s36, s54
	s_addc_u32 s37, s37, 0
	v_mov_b32_e32 v248, 1
	s_mov_b32 s55, 0x100000
	global_atomic_add v1, v248, s[36:37]

.Lln2_xdone:
	s_or_b64 exec, exec, s[48:49]
	s_barrier
	global_load_dwordx2 v[226:227], v247, s[34:35] sc1
	s_add_u32 s34, s34, 0xc000
	s_addc_u32 s35, s35, 0
	global_load_dwordx2 v[228:229], v247, s[34:35] sc1
	s_add_u32 s34, s34, 0xc000
	s_addc_u32 s35, s35, 0
	global_load_dwordx2 v[230:231], v247, s[34:35] sc1
	s_add_u32 s34, s34, 0xc000
	s_addc_u32 s35, s35, 0
	global_load_dwordx2 v[232:233], v247, s[34:35] sc1
	s_add_u32 s34, s34, 0xc000
	s_addc_u32 s35, s35, 0
	global_load_dwordx2 v[234:235], v247, s[34:35] sc1
	s_add_u32 s34, s34, 0xc000
	s_addc_u32 s35, s35, 0
	global_load_dwordx2 v[236:237], v247, s[34:35] sc1
	s_add_u32 s34, s34, 0xc000
	s_addc_u32 s35, s35, 0
	global_load_dwordx2 v[238:239], v247, s[34:35] sc1
	s_add_u32 s34, s34, 0xc000
	s_addc_u32 s35, s35, 0
	global_load_dwordx2 v[240:241], v247, s[34:35] sc1
	s_add_u32 s34, s34, 0xc000
	s_addc_u32 s35, s35, 0
	global_load_dwordx2 v[38:39], v247, s[34:35] sc1
	s_add_u32 s34, s34, 0xc000
	s_addc_u32 s35, s35, 0
	global_load_dwordx2 v[40:41], v247, s[34:35] sc1
	s_add_u32 s34, s34, 0xc000
	s_addc_u32 s35, s35, 0
	global_load_dwordx2 v[42:43], v247, s[34:35] sc1
	s_add_u32 s34, s34, 0xc000
	s_addc_u32 s35, s35, 0
	global_load_dwordx2 v[44:45], v247, s[34:35] sc1
	s_add_u32 s34, s34, 0xc000
	s_addc_u32 s35, s35, 0
	global_load_dwordx2 v[46:47], v247, s[34:35] sc1
	s_add_u32 s34, s34, 0xc000
	s_addc_u32 s35, s35, 0
	global_load_dwordx2 v[48:49], v247, s[34:35] sc1
	s_add_u32 s34, s34, 0xc000
	s_addc_u32 s35, s35, 0
	global_load_dwordx2 v[50:51], v247, s[34:35] sc1
	s_add_u32 s34, s34, 0xc000
	s_addc_u32 s35, s35, 0
	global_load_dwordx2 v[52:53], v247, s[34:35] sc1
	s_waitcnt vmcnt(0)
	v_add_f32_e32 v206, 0, v226
	v_add_f32_e32 v207, 0, v227
	v_add_f32_e32 v206, v206, v228
	v_add_f32_e32 v207, v207, v229
	v_add_f32_e32 v206, v206, v230
	v_add_f32_e32 v207, v207, v231
	v_add_f32_e32 v206, v206, v232
	v_add_f32_e32 v207, v207, v233
	v_add_f32_e32 v206, v206, v234
	v_add_f32_e32 v207, v207, v235
	v_add_f32_e32 v206, v206, v236
	v_add_f32_e32 v207, v207, v237
	v_add_f32_e32 v206, v206, v238
	v_add_f32_e32 v207, v207, v239
	v_add_f32_e32 v206, v206, v240
	v_add_f32_e32 v207, v207, v241
	v_add_f32_e32 v206, v206, v38
	v_add_f32_e32 v207, v207, v39
	v_add_f32_e32 v206, v206, v40
	v_add_f32_e32 v207, v207, v41
	v_add_f32_e32 v206, v206, v42
	v_add_f32_e32 v207, v207, v43
	v_add_f32_e32 v206, v206, v44
	v_add_f32_e32 v207, v207, v45
	v_add_f32_e32 v206, v206, v46
	v_add_f32_e32 v207, v207, v47
	v_add_f32_e32 v206, v206, v48
	v_add_f32_e32 v207, v207, v49
	v_add_f32_e32 v206, v206, v50
	v_add_f32_e32 v207, v207, v51
	v_add_f32_e32 v206, v206, v52
	v_add_f32_e32 v207, v207, v53
	s_add_u32 s22, s22, 0x12000
	s_addc_u32 s23, s23, 0
	s_cmp_eq_u32 s53, 3
	s_cbranch_scc1 .Lln2_nomod
	s_add_i32 s54, s51, 0
	s_lshl_b32 s54, s54, 2
	v_lshl_add_u32 v222, v252, 4, s54
	v_add_u32_e32 v246, 0x1000, v222
	global_load_dwordx4 v[226:229], v222, s[22:23]
	global_load_dwordx4 v[230:233], v222, s[22:23] offset:64
	global_load_dwordx4 v[234:237], v222, s[22:23] offset:128
	global_load_dwordx4 v[238:241], v222, s[22:23] offset:192
	global_load_dwordx4 v[38:41], v246, s[22:23]
	global_load_dwordx4 v[42:45], v246, s[22:23] offset:64
	global_load_dwordx4 v[46:49], v246, s[22:23] offset:128
	global_load_dwordx4 v[50:53], v246, s[22:23] offset:192
